# rwkv_post loop hand-written: 32 loads in flight per iteration instead of serialized load/wait pairs (plus scan/staging rewrite, P2 load hoisting, MODE1 preloads)
# speedup vs baseline: 1.0510x; 1.0337x over previous
; DI int tidx() { int t = threadIdx.x; asm volatile("" : "+v"(t)); return t; }
; DI int bidx() { int b = blockIdx.x; asm volatile("" : "+s"(b)); return b; }
; DI char* WS(const Params&) { return *(char* const __attribute__((address_space(4)))*)(KA() + 8 * 30); }
; #define TE(k) do { if (PROBE_T == (k)) tacc += __builtin_amdgcn_s_memrealtime() - t0; } while (0)
; __global__ void __launch_bounds__(512, 2) fwd_megakernel(Params p) {
;     ...
;       int* cnt = (int*)(WS(p) + O_CNT) + l;
;       if (tidx() == 0) *(int*)(smraw + DYN_XB + 20) = 0;
;       __syncthreads();
;       for (int it = bidx(); it < 128; it += gridDim.x) rwkv_scan(p, it, smraw);
;       TE(18);
;       while (true) {
;         if (tidx() == 0) *s_item = atomicAdd(cnt, 1);
.LBB0_491:
	v_mov_b32_e32 v245, 0
	v_readlane_b32 s0, v252, 52
	v_readlane_b32 s1, v252, 53
	s_mov_b32 s2, s68
	s_mov_b32 s3, s1
	s_lshl_b64 s[4:5], s[2:3], 2
	s_add_u32 s0, s8, s4
	v_writelane_b32 v252, s4, 54
	s_addc_u32 s1, s9, s5
	s_add_u32 s0, s0, 0x12a0400
	v_writelane_b32 v252, s5, 55
	s_addc_u32 s1, s1, 0
	v_writelane_b32 v252, s0, 56
	s_nop 1
	v_writelane_b32 v252, s1, 57
	s_mov_b32 s0, s68
	v_writelane_b32 v252, s0, 58
	s_nop 1
	v_writelane_b32 v252, s1, 59
	s_lshl_b32 s0, s68, 2
	v_writelane_b32 v252, s0, 60
	s_branch .LBB0_514

; DI float row16_sum(float x) { x = dpp_add(x, 0); x = dpp_add(x, 1); x = dpp_add(x, 2); x = dpp_add(x, 3); return x; }
; DI void rwkv_scan(const Params& p, int item, char* smraw) {
;     ...
;   for (int ch = 0; ch < 128; ++ch) {
;     if (comp) {
;       int nxt = cur + 1; if (nxt == 3) nxt = 0;
;       const float* st = stage + cur * 16 * 384 + 4 * kq;
;       const float* sv = stage + cur * 16 * 384 + 3 * 64 + 16 * rg + row;
;       const float* stn = stage + nxt * 16 * 384 + 4 * kq;
;       const float* svn = stage + nxt * 16 * 384 + 3 * 64 + 16 * rg + row;
; #pragma unroll
;       for (int s = 0; s < 16; ++s) {
;         float4 cr, cw, ck, ca, cb; float cv;
;         if (s & 1) { cr = Pr1; cw = Pw1; ck = Pk1; ca = Pa1; cb = Pb1; cv = Pv1; }
;         else { cr = Pr0; cw = Pw0; ck = Pk0; ca = Pa0; cb = Pb0; cv = Pv0; }
;         {
;           const float* sp = (s < 14) ? (st + (s + 2) * 384) : (stn + (s - 14) * 384);
;           const float* vp = (s < 14) ? (sv + (s + 2) * 384) : (svn + (s - 14) * 384);
;           if (s & 1) { Pr1 = *(const float4*)(sp + 0 * 64); Pw1 = *(const float4*)(sp + 1 * 64); Pk1 = *(const float4*)(sp + 2 * 64); Pa1 = *(const float4*)(sp + 4 * 64); Pb1 = *(const float4*)(sp + 5 * 64); Pv1 = vp[0]; }
;           else { Pr0 = *(const float4*)(sp + 0 * 64); Pw0 = *(const float4*)(sp + 1 * 64); Pk0 = *(const float4*)(sp + 2 * 64); Pa0 = *(const float4*)(sp + 4 * 64); Pb0 = *(const float4*)(sp + 5 * 64); Pv0 = vp[0]; }
;         }
;         const fv2 a01 = {ca.x, ca.y}, a23 = {ca.z, ca.w}, w01 = {cw.x, cw.y}, w23 = {cw.z, cw.w};
;         const fv2 k01 = {ck.x, ck.y}, k23 = {ck.z, ck.w}, b01 = {cb.x, cb.y}, b23 = {cb.z, cb.w};
;         const fv2 r01 = {cr.x, cr.y}, r23 = {cr.z, cr.w};
;         const fv2 vv = {cv, cv};
;         fv2 pa = S01 * a01; pa = __builtin_elementwise_fma(S23, a23, pa);
;         float sa = pa.x + pa.y;
;         const fv2 t01 = __builtin_elementwise_fma(S01, w01, vv * k01);
;         const fv2 t23 = __builtin_elementwise_fma(S23, w23, vv * k23);
;         sa = row16_sum(sa);
;         const fv2 sav = {sa, sa};
;         S01 = __builtin_elementwise_fma(sav, b01, t01);
;         S23 = __builtin_elementwise_fma(sav, b23, t23);
;         fv2 py = S01 * r01; py = __builtin_elementwise_fma(S23, r23, py);
;         ypart[(ch & 1) * 4096 + s * 256 + tid] = py.x + py.y;
.Lsc_top:
	v_pk_mul_f32 v[118:119], v[64:65], v[26:27]
	v_pk_mul_f32 v[22:23], v[22:23], v[62:63] op_sel_hi:[1,0]
	v_pk_fma_f32 v[118:119], v[66:67], v[28:29], v[118:119]
	v_pk_mul_f32 v[24:25], v[24:25], v[62:63] op_sel_hi:[1,0]
	v_pk_fma_f32 v[18:19], v[64:65], v[18:19], v[22:23]
	v_add_f32_e32 v118, v118, v119
	v_pk_fma_f32 v[20:21], v[66:67], v[20:21], v[24:25]
	ds_read2st64_b32 v[116:117], v125 offset0:15 offset1:21
	v_add_f32_dpp v118, v118, v118 quad_perm:[1,0,3,2] row_mask:0xf bank_mask:0xf bound_ctrl:1
	ds_read_b128 v[88:91], v124 offset:4096
	ds_read_b128 v[84:87], v124 offset:3584
	v_add_f32_dpp v118, v118, v118 quad_perm:[2,3,0,1] row_mask:0xf bank_mask:0xf bound_ctrl:1
	ds_read_b128 v[80:83], v124 offset:3328
	ds_read_b128 v[92:95], v124 offset:4352
	v_add_f32_dpp v118, v118, v118 row_half_mirror row_mask:0xf bank_mask:0xf bound_ctrl:1
	ds_read_b128 v[76:79], v124 offset:3072
	s_nop 0
	v_add_f32_dpp v118, v118, v118 row_mirror row_mask:0xf bank_mask:0xf bound_ctrl:1
	v_pk_fma_f32 v[64:65], v[118:119], v[30:31], v[18:19] op_sel_hi:[0,1,1]
	v_pk_fma_f32 v[66:67], v[118:119], v[32:33], v[20:21] op_sel_hi:[0,1,1]
	v_pk_mul_f32 v[118:119], v[64:65], v[50:51]
	v_pk_mul_f32 v[46:47], v[46:47], v[62:63] op_sel:[0,1] op_sel_hi:[1,1]
	v_pk_fma_f32 v[118:119], v[66:67], v[52:53], v[118:119]
	v_pk_mul_f32 v[48:49], v[48:49], v[62:63] op_sel:[0,1] op_sel_hi:[1,1]
	v_pk_fma_f32 v[42:43], v[64:65], v[42:43], v[46:47]
	v_add_f32_e32 v118, v118, v119
	v_pk_fma_f32 v[44:45], v[66:67], v[44:45], v[48:49]
	v_pk_mul_f32 v[120:121], v[64:65], v[14:15]
	v_add_f32_dpp v118, v118, v118 quad_perm:[1,0,3,2] row_mask:0xf bank_mask:0xf bound_ctrl:1
	v_pk_fma_f32 v[120:121], v[66:67], v[16:17], v[120:121]
	ds_read_b128 v[108:111], v124 offset:5632
	v_add_f32_dpp v118, v118, v118 quad_perm:[2,3,0,1] row_mask:0xf bank_mask:0xf bound_ctrl:1
	v_add_f32_e32 v122, v120, v121
	ds_read_b128 v[104:107], v124 offset:5120
	v_add_f32_dpp v118, v118, v118 row_half_mirror row_mask:0xf bank_mask:0xf bound_ctrl:1
	ds_read_b128 v[100:103], v124 offset:4864
	ds_read_b128 v[112:115], v124 offset:5888
	v_add_f32_dpp v118, v118, v118 row_mirror row_mask:0xf bank_mask:0xf bound_ctrl:1
	v_pk_fma_f32 v[64:65], v[118:119], v[38:39], v[42:43] op_sel_hi:[0,1,1]
	v_pk_fma_f32 v[66:67], v[118:119], v[40:41], v[44:45] op_sel_hi:[0,1,1]
	ds_read_b128 v[96:99], v124 offset:4608
	s_waitcnt lgkmcnt(5)
	v_pk_mul_f32 v[118:119], v[64:65], v[88:89]
	v_pk_mul_f32 v[84:85], v[84:85], v[116:117] op_sel_hi:[1,0]
	v_pk_fma_f32 v[118:119], v[66:67], v[90:91], v[118:119]
	v_pk_mul_f32 v[86:87], v[86:87], v[116:117] op_sel_hi:[1,0]
	v_pk_fma_f32 v[80:81], v[64:65], v[80:81], v[84:85]
	v_add_f32_e32 v118, v118, v119
	v_pk_fma_f32 v[82:83], v[66:67], v[82:83], v[86:87]
	v_pk_mul_f32 v[120:121], v[64:65], v[34:35]
	v_add_f32_dpp v118, v118, v118 quad_perm:[1,0,3,2] row_mask:0xf bank_mask:0xf bound_ctrl:1
	v_pk_fma_f32 v[120:121], v[66:67], v[36:37], v[120:121]
	ds_read2st64_b32 v[62:63], v125 offset0:27 offset1:33
	v_add_f32_dpp v118, v118, v118 quad_perm:[2,3,0,1] row_mask:0xf bank_mask:0xf bound_ctrl:1
	v_add_f32_e32 v123, v120, v121
	ds_read_b128 v[26:29], v124 offset:7168
	v_add_f32_dpp v118, v118, v118 row_half_mirror row_mask:0xf bank_mask:0xf bound_ctrl:1
	ds_read_b128 v[22:25], v124 offset:6656
	ds_read_b128 v[18:21], v124 offset:6400
	v_add_f32_dpp v118, v118, v118 row_mirror row_mask:0xf bank_mask:0xf bound_ctrl:1
	v_pk_fma_f32 v[64:65], v[118:119], v[92:93], v[80:81] op_sel_hi:[0,1,1]
	v_pk_fma_f32 v[66:67], v[118:119], v[94:95], v[82:83] op_sel_hi:[0,1,1]
	ds_read_b128 v[30:33], v124 offset:7424
	ds_read_b128 v[14:17], v124 offset:6144
	ds_write2st64_b32 v128, v122, v123 offset0:0 offset1:4
	s_waitcnt lgkmcnt(7)
	v_pk_mul_f32 v[118:119], v[64:65], v[108:109]
	v_pk_mul_f32 v[104:105], v[104:105], v[116:117] op_sel:[0,1] op_sel_hi:[1,1]
	v_pk_fma_f32 v[118:119], v[66:67], v[110:111], v[118:119]
	v_pk_mul_f32 v[106:107], v[106:107], v[116:117] op_sel:[0,1] op_sel_hi:[1,1]
	v_pk_fma_f32 v[100:101], v[64:65], v[100:101], v[104:105]
	v_add_f32_e32 v118, v118, v119
	v_pk_fma_f32 v[102:103], v[66:67], v[102:103], v[106:107]
	v_pk_mul_f32 v[120:121], v[64:65], v[76:77]
	v_add_f32_dpp v118, v118, v118 quad_perm:[1,0,3,2] row_mask:0xf bank_mask:0xf bound_ctrl:1
	v_pk_fma_f32 v[120:121], v[66:67], v[78:79], v[120:121]
	ds_read_b128 v[50:53], v124 offset:8704
	v_add_f32_dpp v118, v118, v118 quad_perm:[2,3,0,1] row_mask:0xf bank_mask:0xf bound_ctrl:1
	v_add_f32_e32 v122, v120, v121
	ds_read_b128 v[46:49], v124 offset:8192
	v_add_f32_dpp v118, v118, v118 row_half_mirror row_mask:0xf bank_mask:0xf bound_ctrl:1
	ds_read_b128 v[42:45], v124 offset:7936
	ds_read_b128 v[38:41], v124 offset:8960
	v_add_f32_dpp v118, v118, v118 row_mirror row_mask:0xf bank_mask:0xf bound_ctrl:1
	v_pk_fma_f32 v[64:65], v[118:119], v[112:113], v[100:101] op_sel_hi:[0,1,1]
	v_pk_fma_f32 v[66:67], v[118:119], v[114:115], v[102:103] op_sel_hi:[0,1,1]
	ds_read_b128 v[34:37], v124 offset:7680
	s_waitcnt lgkmcnt(6)
; DI float row16_sum(float x) { x = dpp_add(x, 0); x = dpp_add(x, 1); x = dpp_add(x, 2); x = dpp_add(x, 3); return x; }
; DI void rwkv_scan(const Params& p, int item, char* smraw) {
;     ...
;       for (int s = 0; s < 16; ++s) {
;         float4 cr, cw, ck, ca, cb; float cv;
;         if (s & 1) { cr = Pr1; cw = Pw1; ck = Pk1; ca = Pa1; cb = Pb1; cv = Pv1; }
;         else { cr = Pr0; cw = Pw0; ck = Pk0; ca = Pa0; cb = Pb0; cv = Pv0; }
;         {
;           const float* sp = (s < 14) ? (st + (s + 2) * 384) : (stn + (s - 14) * 384);
;           const float* vp = (s < 14) ? (sv + (s + 2) * 384) : (svn + (s - 14) * 384);
;           if (s & 1) { Pr1 = *(const float4*)(sp + 0 * 64); Pw1 = *(const float4*)(sp + 1 * 64); Pk1 = *(const float4*)(sp + 2 * 64); Pa1 = *(const float4*)(sp + 4 * 64); Pb1 = *(const float4*)(sp + 5 * 64); Pv1 = vp[0]; }
;           else { Pr0 = *(const float4*)(sp + 0 * 64); Pw0 = *(const float4*)(sp + 1 * 64); Pk0 = *(const float4*)(sp + 2 * 64); Pa0 = *(const float4*)(sp + 4 * 64); Pb0 = *(const float4*)(sp + 5 * 64); Pv0 = vp[0]; }
;         }
;         const fv2 a01 = {ca.x, ca.y}, a23 = {ca.z, ca.w}, w01 = {cw.x, cw.y}, w23 = {cw.z, cw.w};
;         const fv2 k01 = {ck.x, ck.y}, k23 = {ck.z, ck.w}, b01 = {cb.x, cb.y}, b23 = {cb.z, cb.w};
;         const fv2 r01 = {cr.x, cr.y}, r23 = {cr.z, cr.w};
;         const fv2 vv = {cv, cv};
;         fv2 pa = S01 * a01; pa = __builtin_elementwise_fma(S23, a23, pa);
;         float sa = pa.x + pa.y;
;         const fv2 t01 = __builtin_elementwise_fma(S01, w01, vv * k01);
;         const fv2 t23 = __builtin_elementwise_fma(S23, w23, vv * k23);
;         sa = row16_sum(sa);
;         const fv2 sav = {sa, sa};
;         S01 = __builtin_elementwise_fma(sav, b01, t01);
;         S23 = __builtin_elementwise_fma(sav, b23, t23);
;         fv2 py = S01 * r01; py = __builtin_elementwise_fma(S23, r23, py);
;         ypart[(ch & 1) * 4096 + s * 256 + tid] = py.x + py.y;
	v_pk_mul_f32 v[118:119], v[64:65], v[26:27]
	v_pk_mul_f32 v[22:23], v[22:23], v[62:63] op_sel_hi:[1,0]
	v_pk_fma_f32 v[118:119], v[66:67], v[28:29], v[118:119]
	v_pk_mul_f32 v[24:25], v[24:25], v[62:63] op_sel_hi:[1,0]
	v_pk_fma_f32 v[18:19], v[64:65], v[18:19], v[22:23]
	v_add_f32_e32 v118, v118, v119
	v_pk_fma_f32 v[20:21], v[66:67], v[20:21], v[24:25]
	v_pk_mul_f32 v[120:121], v[64:65], v[96:97]
	v_add_f32_dpp v118, v118, v118 quad_perm:[1,0,3,2] row_mask:0xf bank_mask:0xf bound_ctrl:1
	v_pk_fma_f32 v[120:121], v[66:67], v[98:99], v[120:121]
	ds_read2st64_b32 v[116:117], v125 offset0:39 offset1:45
	v_add_f32_dpp v118, v118, v118 quad_perm:[2,3,0,1] row_mask:0xf bank_mask:0xf bound_ctrl:1
	v_add_f32_e32 v123, v120, v121
	ds_read_b128 v[88:91], v124 offset:10240
	v_add_f32_dpp v118, v118, v118 row_half_mirror row_mask:0xf bank_mask:0xf bound_ctrl:1
	ds_read_b128 v[84:87], v124 offset:9728
	ds_read_b128 v[80:83], v124 offset:9472
	v_add_f32_dpp v118, v118, v118 row_mirror row_mask:0xf bank_mask:0xf bound_ctrl:1
	v_pk_fma_f32 v[64:65], v[118:119], v[30:31], v[18:19] op_sel_hi:[0,1,1]
	v_pk_fma_f32 v[66:67], v[118:119], v[32:33], v[20:21] op_sel_hi:[0,1,1]
	ds_read_b128 v[92:95], v124 offset:10496
	ds_read_b128 v[76:79], v124 offset:9216
	ds_write2st64_b32 v128, v122, v123 offset0:8 offset1:12
	s_waitcnt lgkmcnt(7)
	v_pk_mul_f32 v[118:119], v[64:65], v[50:51]
	v_pk_mul_f32 v[46:47], v[46:47], v[62:63] op_sel:[0,1] op_sel_hi:[1,1]
	v_pk_fma_f32 v[118:119], v[66:67], v[52:53], v[118:119]
	v_pk_mul_f32 v[48:49], v[48:49], v[62:63] op_sel:[0,1] op_sel_hi:[1,1]
	v_pk_fma_f32 v[42:43], v[64:65], v[42:43], v[46:47]
	v_add_f32_e32 v118, v118, v119
	v_pk_fma_f32 v[44:45], v[66:67], v[44:45], v[48:49]
	v_pk_mul_f32 v[120:121], v[64:65], v[14:15]
	v_add_f32_dpp v118, v118, v118 quad_perm:[1,0,3,2] row_mask:0xf bank_mask:0xf bound_ctrl:1
	v_pk_fma_f32 v[120:121], v[66:67], v[16:17], v[120:121]
	ds_read_b128 v[108:111], v124 offset:11776
	v_add_f32_dpp v118, v118, v118 quad_perm:[2,3,0,1] row_mask:0xf bank_mask:0xf bound_ctrl:1
	v_add_f32_e32 v122, v120, v121
	ds_read_b128 v[104:107], v124 offset:11264
	v_add_f32_dpp v118, v118, v118 row_half_mirror row_mask:0xf bank_mask:0xf bound_ctrl:1
	ds_read_b128 v[100:103], v124 offset:11008
	ds_read_b128 v[112:115], v124 offset:12032
	v_add_f32_dpp v118, v118, v118 row_mirror row_mask:0xf bank_mask:0xf bound_ctrl:1
	v_pk_fma_f32 v[64:65], v[118:119], v[38:39], v[42:43] op_sel_hi:[0,1,1]
	v_pk_fma_f32 v[66:67], v[118:119], v[40:41], v[44:45] op_sel_hi:[0,1,1]
	ds_read_b128 v[96:99], v124 offset:10752
	s_waitcnt lgkmcnt(6)
	v_pk_mul_f32 v[118:119], v[64:65], v[88:89]
	v_pk_mul_f32 v[84:85], v[84:85], v[116:117] op_sel_hi:[1,0]
	v_pk_fma_f32 v[118:119], v[66:67], v[90:91], v[118:119]
	v_pk_mul_f32 v[86:87], v[86:87], v[116:117] op_sel_hi:[1,0]
	v_pk_fma_f32 v[80:81], v[64:65], v[80:81], v[84:85]
	v_add_f32_e32 v118, v118, v119
	v_pk_fma_f32 v[82:83], v[66:67], v[82:83], v[86:87]
	v_pk_mul_f32 v[120:121], v[64:65], v[34:35]
	v_add_f32_dpp v118, v118, v118 quad_perm:[1,0,3,2] row_mask:0xf bank_mask:0xf bound_ctrl:1
	v_pk_fma_f32 v[120:121], v[66:67], v[36:37], v[120:121]
	ds_read2st64_b32 v[62:63], v125 offset0:51 offset1:57
	v_add_f32_dpp v118, v118, v118 quad_perm:[2,3,0,1] row_mask:0xf bank_mask:0xf bound_ctrl:1
	v_add_f32_e32 v123, v120, v121
	ds_read_b128 v[26:29], v124 offset:13312
	v_add_f32_dpp v118, v118, v118 row_half_mirror row_mask:0xf bank_mask:0xf bound_ctrl:1
	ds_read_b128 v[22:25], v124 offset:12800
	ds_read_b128 v[18:21], v124 offset:12544
	v_add_f32_dpp v118, v118, v118 row_mirror row_mask:0xf bank_mask:0xf bound_ctrl:1
	v_pk_fma_f32 v[64:65], v[118:119], v[92:93], v[80:81] op_sel_hi:[0,1,1]
	v_pk_fma_f32 v[66:67], v[118:119], v[94:95], v[82:83] op_sel_hi:[0,1,1]
	ds_read_b128 v[30:33], v124 offset:13568
	ds_read_b128 v[14:17], v124 offset:12288
	ds_write2st64_b32 v128, v122, v123 offset0:16 offset1:20
	s_waitcnt lgkmcnt(7)
	v_pk_mul_f32 v[118:119], v[64:65], v[108:109]
	v_pk_mul_f32 v[104:105], v[104:105], v[116:117] op_sel:[0,1] op_sel_hi:[1,1]
	v_pk_fma_f32 v[118:119], v[66:67], v[110:111], v[118:119]
	v_pk_mul_f32 v[106:107], v[106:107], v[116:117] op_sel:[0,1] op_sel_hi:[1,1]
	v_pk_fma_f32 v[100:101], v[64:65], v[100:101], v[104:105]
	v_add_f32_e32 v118, v118, v119
	v_pk_fma_f32 v[102:103], v[66:67], v[102:103], v[106:107]
	v_pk_mul_f32 v[120:121], v[64:65], v[76:77]
	v_add_f32_dpp v118, v118, v118 quad_perm:[1,0,3,2] row_mask:0xf bank_mask:0xf bound_ctrl:1
	v_pk_fma_f32 v[120:121], v[66:67], v[78:79], v[120:121]
	ds_read_b128 v[50:53], v124 offset:14848
	v_add_f32_dpp v118, v118, v118 quad_perm:[2,3,0,1] row_mask:0xf bank_mask:0xf bound_ctrl:1
	v_add_f32_e32 v122, v120, v121
	ds_read_b128 v[46:49], v124 offset:14336
	v_add_f32_dpp v118, v118, v118 row_half_mirror row_mask:0xf bank_mask:0xf bound_ctrl:1
	ds_read_b128 v[42:45], v124 offset:14080
	ds_read_b128 v[38:41], v124 offset:15104
	v_add_f32_dpp v118, v118, v118 row_mirror row_mask:0xf bank_mask:0xf bound_ctrl:1
	v_pk_fma_f32 v[64:65], v[118:119], v[112:113], v[100:101] op_sel_hi:[0,1,1]
	v_pk_fma_f32 v[66:67], v[118:119], v[114:115], v[102:103] op_sel_hi:[0,1,1]
	ds_read_b128 v[34:37], v124 offset:13824
	s_waitcnt lgkmcnt(6)
; DI float row16_sum(float x) { x = dpp_add(x, 0); x = dpp_add(x, 1); x = dpp_add(x, 2); x = dpp_add(x, 3); return x; }
; DI void rwkv_scan(const Params& p, int item, char* smraw) {
;     ...
;       for (int s = 0; s < 16; ++s) {
;         float4 cr, cw, ck, ca, cb; float cv;
;         if (s & 1) { cr = Pr1; cw = Pw1; ck = Pk1; ca = Pa1; cb = Pb1; cv = Pv1; }
;         else { cr = Pr0; cw = Pw0; ck = Pk0; ca = Pa0; cb = Pb0; cv = Pv0; }
;         {
;           const float* sp = (s < 14) ? (st + (s + 2) * 384) : (stn + (s - 14) * 384);
;           const float* vp = (s < 14) ? (sv + (s + 2) * 384) : (svn + (s - 14) * 384);
;           if (s & 1) { Pr1 = *(const float4*)(sp + 0 * 64); Pw1 = *(const float4*)(sp + 1 * 64); Pk1 = *(const float4*)(sp + 2 * 64); Pa1 = *(const float4*)(sp + 4 * 64); Pb1 = *(const float4*)(sp + 5 * 64); Pv1 = vp[0]; }
;           else { Pr0 = *(const float4*)(sp + 0 * 64); Pw0 = *(const float4*)(sp + 1 * 64); Pk0 = *(const float4*)(sp + 2 * 64); Pa0 = *(const float4*)(sp + 4 * 64); Pb0 = *(const float4*)(sp + 5 * 64); Pv0 = vp[0]; }
;         }
;         const fv2 a01 = {ca.x, ca.y}, a23 = {ca.z, ca.w}, w01 = {cw.x, cw.y}, w23 = {cw.z, cw.w};
;         const fv2 k01 = {ck.x, ck.y}, k23 = {ck.z, ck.w}, b01 = {cb.x, cb.y}, b23 = {cb.z, cb.w};
;         const fv2 r01 = {cr.x, cr.y}, r23 = {cr.z, cr.w};
;         const fv2 vv = {cv, cv};
;         fv2 pa = S01 * a01; pa = __builtin_elementwise_fma(S23, a23, pa);
;         float sa = pa.x + pa.y;
;         const fv2 t01 = __builtin_elementwise_fma(S01, w01, vv * k01);
;         const fv2 t23 = __builtin_elementwise_fma(S23, w23, vv * k23);
;         sa = row16_sum(sa);
;         const fv2 sav = {sa, sa};
;         S01 = __builtin_elementwise_fma(sav, b01, t01);
;         S23 = __builtin_elementwise_fma(sav, b23, t23);
;         fv2 py = S01 * r01; py = __builtin_elementwise_fma(S23, r23, py);
;         ypart[(ch & 1) * 4096 + s * 256 + tid] = py.x + py.y;
	v_pk_mul_f32 v[118:119], v[64:65], v[26:27]
	v_pk_mul_f32 v[22:23], v[22:23], v[62:63] op_sel_hi:[1,0]
	v_pk_fma_f32 v[118:119], v[66:67], v[28:29], v[118:119]
	v_pk_mul_f32 v[24:25], v[24:25], v[62:63] op_sel_hi:[1,0]
	v_pk_fma_f32 v[18:19], v[64:65], v[18:19], v[22:23]
	v_add_f32_e32 v118, v118, v119
	v_pk_fma_f32 v[20:21], v[66:67], v[20:21], v[24:25]
	v_pk_mul_f32 v[120:121], v[64:65], v[96:97]
	v_add_f32_dpp v118, v118, v118 quad_perm:[1,0,3,2] row_mask:0xf bank_mask:0xf bound_ctrl:1
	v_pk_fma_f32 v[120:121], v[66:67], v[98:99], v[120:121]
	ds_read2st64_b32 v[116:117], v125 offset0:63 offset1:69
	v_add_f32_dpp v118, v118, v118 quad_perm:[2,3,0,1] row_mask:0xf bank_mask:0xf bound_ctrl:1
	v_add_f32_e32 v123, v120, v121
	ds_read_b128 v[88:91], v124 offset:16384
	v_add_f32_dpp v118, v118, v118 row_half_mirror row_mask:0xf bank_mask:0xf bound_ctrl:1
	ds_read_b128 v[84:87], v124 offset:15872
	ds_read_b128 v[80:83], v124 offset:15616
	v_add_f32_dpp v118, v118, v118 row_mirror row_mask:0xf bank_mask:0xf bound_ctrl:1
	v_pk_fma_f32 v[64:65], v[118:119], v[30:31], v[18:19] op_sel_hi:[0,1,1]
	v_pk_fma_f32 v[66:67], v[118:119], v[32:33], v[20:21] op_sel_hi:[0,1,1]
	ds_read_b128 v[92:95], v124 offset:16640
	ds_read_b128 v[76:79], v124 offset:15360
	ds_write2st64_b32 v128, v122, v123 offset0:24 offset1:28
	s_waitcnt lgkmcnt(7)
	v_pk_mul_f32 v[118:119], v[64:65], v[50:51]
	v_pk_mul_f32 v[46:47], v[46:47], v[62:63] op_sel:[0,1] op_sel_hi:[1,1]
	v_pk_fma_f32 v[118:119], v[66:67], v[52:53], v[118:119]
	v_pk_mul_f32 v[48:49], v[48:49], v[62:63] op_sel:[0,1] op_sel_hi:[1,1]
	v_pk_fma_f32 v[42:43], v[64:65], v[42:43], v[46:47]
	v_add_f32_e32 v118, v118, v119
	v_pk_fma_f32 v[44:45], v[66:67], v[44:45], v[48:49]
	v_pk_mul_f32 v[120:121], v[64:65], v[14:15]
	v_add_f32_dpp v118, v118, v118 quad_perm:[1,0,3,2] row_mask:0xf bank_mask:0xf bound_ctrl:1
	v_pk_fma_f32 v[120:121], v[66:67], v[16:17], v[120:121]
	ds_read_b128 v[108:111], v124 offset:17920
	v_add_f32_dpp v118, v118, v118 quad_perm:[2,3,0,1] row_mask:0xf bank_mask:0xf bound_ctrl:1
	v_add_f32_e32 v122, v120, v121
	ds_read_b128 v[104:107], v124 offset:17408
	v_add_f32_dpp v118, v118, v118 row_half_mirror row_mask:0xf bank_mask:0xf bound_ctrl:1
	ds_read_b128 v[100:103], v124 offset:17152
	ds_read_b128 v[112:115], v124 offset:18176
	v_add_f32_dpp v118, v118, v118 row_mirror row_mask:0xf bank_mask:0xf bound_ctrl:1
	v_pk_fma_f32 v[64:65], v[118:119], v[38:39], v[42:43] op_sel_hi:[0,1,1]
	v_pk_fma_f32 v[66:67], v[118:119], v[40:41], v[44:45] op_sel_hi:[0,1,1]
	ds_read_b128 v[96:99], v124 offset:16896
	s_waitcnt lgkmcnt(6)
	v_pk_mul_f32 v[118:119], v[64:65], v[88:89]
	v_pk_mul_f32 v[84:85], v[84:85], v[116:117] op_sel_hi:[1,0]
	v_pk_fma_f32 v[118:119], v[66:67], v[90:91], v[118:119]
	v_pk_mul_f32 v[86:87], v[86:87], v[116:117] op_sel_hi:[1,0]
	v_pk_fma_f32 v[80:81], v[64:65], v[80:81], v[84:85]
	v_add_f32_e32 v118, v118, v119
	v_pk_fma_f32 v[82:83], v[66:67], v[82:83], v[86:87]
	v_pk_mul_f32 v[120:121], v[64:65], v[34:35]
	v_add_f32_dpp v118, v118, v118 quad_perm:[1,0,3,2] row_mask:0xf bank_mask:0xf bound_ctrl:1
	v_pk_fma_f32 v[120:121], v[66:67], v[36:37], v[120:121]
	ds_read2st64_b32 v[62:63], v125 offset0:75 offset1:81
	v_add_f32_dpp v118, v118, v118 quad_perm:[2,3,0,1] row_mask:0xf bank_mask:0xf bound_ctrl:1
	v_add_f32_e32 v123, v120, v121
	ds_read_b128 v[26:29], v124 offset:19456
	v_add_f32_dpp v118, v118, v118 row_half_mirror row_mask:0xf bank_mask:0xf bound_ctrl:1
	ds_read_b128 v[22:25], v124 offset:18944
	ds_read_b128 v[18:21], v124 offset:18688
	v_add_f32_dpp v118, v118, v118 row_mirror row_mask:0xf bank_mask:0xf bound_ctrl:1
	v_pk_fma_f32 v[64:65], v[118:119], v[92:93], v[80:81] op_sel_hi:[0,1,1]
	v_pk_fma_f32 v[66:67], v[118:119], v[94:95], v[82:83] op_sel_hi:[0,1,1]
	ds_read_b128 v[30:33], v124 offset:19712
	ds_read_b128 v[14:17], v124 offset:18432
	ds_write2st64_b32 v128, v122, v123 offset0:32 offset1:36
	s_waitcnt lgkmcnt(7)
	v_pk_mul_f32 v[118:119], v[64:65], v[108:109]
	v_pk_mul_f32 v[104:105], v[104:105], v[116:117] op_sel:[0,1] op_sel_hi:[1,1]
	v_pk_fma_f32 v[118:119], v[66:67], v[110:111], v[118:119]
	v_pk_mul_f32 v[106:107], v[106:107], v[116:117] op_sel:[0,1] op_sel_hi:[1,1]
	v_pk_fma_f32 v[100:101], v[64:65], v[100:101], v[104:105]
	v_add_f32_e32 v118, v118, v119
	v_pk_fma_f32 v[102:103], v[66:67], v[102:103], v[106:107]
	v_pk_mul_f32 v[120:121], v[64:65], v[76:77]
	v_add_f32_dpp v118, v118, v118 quad_perm:[1,0,3,2] row_mask:0xf bank_mask:0xf bound_ctrl:1
	v_pk_fma_f32 v[120:121], v[66:67], v[78:79], v[120:121]
	ds_read_b128 v[50:53], v124 offset:20992
	v_add_f32_dpp v118, v118, v118 quad_perm:[2,3,0,1] row_mask:0xf bank_mask:0xf bound_ctrl:1
	v_add_f32_e32 v122, v120, v121
	ds_read_b128 v[46:49], v124 offset:20480
	v_add_f32_dpp v118, v118, v118 row_half_mirror row_mask:0xf bank_mask:0xf bound_ctrl:1
	ds_read_b128 v[42:45], v124 offset:20224
	ds_read_b128 v[38:41], v124 offset:21248
	v_add_f32_dpp v118, v118, v118 row_mirror row_mask:0xf bank_mask:0xf bound_ctrl:1
	v_pk_fma_f32 v[64:65], v[118:119], v[112:113], v[100:101] op_sel_hi:[0,1,1]
	v_pk_fma_f32 v[66:67], v[118:119], v[114:115], v[102:103] op_sel_hi:[0,1,1]
	ds_read_b128 v[34:37], v124 offset:19968
	s_waitcnt lgkmcnt(6)
; DI float row16_sum(float x) { x = dpp_add(x, 0); x = dpp_add(x, 1); x = dpp_add(x, 2); x = dpp_add(x, 3); return x; }
; DI void rwkv_scan(const Params& p, int item, char* smraw) {
;     ...
;       for (int s = 0; s < 16; ++s) {
;         float4 cr, cw, ck, ca, cb; float cv;
;         if (s & 1) { cr = Pr1; cw = Pw1; ck = Pk1; ca = Pa1; cb = Pb1; cv = Pv1; }
;         else { cr = Pr0; cw = Pw0; ck = Pk0; ca = Pa0; cb = Pb0; cv = Pv0; }
;         {
;           const float* sp = (s < 14) ? (st + (s + 2) * 384) : (stn + (s - 14) * 384);
;           const float* vp = (s < 14) ? (sv + (s + 2) * 384) : (svn + (s - 14) * 384);
;           if (s & 1) { Pr1 = *(const float4*)(sp + 0 * 64); Pw1 = *(const float4*)(sp + 1 * 64); Pk1 = *(const float4*)(sp + 2 * 64); Pa1 = *(const float4*)(sp + 4 * 64); Pb1 = *(const float4*)(sp + 5 * 64); Pv1 = vp[0]; }
;           else { Pr0 = *(const float4*)(sp + 0 * 64); Pw0 = *(const float4*)(sp + 1 * 64); Pk0 = *(const float4*)(sp + 2 * 64); Pa0 = *(const float4*)(sp + 4 * 64); Pb0 = *(const float4*)(sp + 5 * 64); Pv0 = vp[0]; }
;         }
;         const fv2 a01 = {ca.x, ca.y}, a23 = {ca.z, ca.w}, w01 = {cw.x, cw.y}, w23 = {cw.z, cw.w};
;         const fv2 k01 = {ck.x, ck.y}, k23 = {ck.z, ck.w}, b01 = {cb.x, cb.y}, b23 = {cb.z, cb.w};
;         const fv2 r01 = {cr.x, cr.y}, r23 = {cr.z, cr.w};
;         const fv2 vv = {cv, cv};
;         fv2 pa = S01 * a01; pa = __builtin_elementwise_fma(S23, a23, pa);
;         float sa = pa.x + pa.y;
;         const fv2 t01 = __builtin_elementwise_fma(S01, w01, vv * k01);
;         const fv2 t23 = __builtin_elementwise_fma(S23, w23, vv * k23);
;         sa = row16_sum(sa);
;         const fv2 sav = {sa, sa};
;         S01 = __builtin_elementwise_fma(sav, b01, t01);
;         S23 = __builtin_elementwise_fma(sav, b23, t23);
;         fv2 py = S01 * r01; py = __builtin_elementwise_fma(S23, r23, py);
;         ypart[(ch & 1) * 4096 + s * 256 + tid] = py.x + py.y;
;     ...
;     __syncthreads();
;     cur = (cur == 2) ? 0 : cur + 1;
;   }
	v_pk_mul_f32 v[118:119], v[64:65], v[26:27]
	v_pk_mul_f32 v[22:23], v[22:23], v[62:63] op_sel_hi:[1,0]
	v_pk_fma_f32 v[118:119], v[66:67], v[28:29], v[118:119]
	v_pk_mul_f32 v[24:25], v[24:25], v[62:63] op_sel_hi:[1,0]
	v_pk_fma_f32 v[18:19], v[64:65], v[18:19], v[22:23]
	v_add_f32_e32 v118, v118, v119
	v_pk_fma_f32 v[20:21], v[66:67], v[20:21], v[24:25]
	v_pk_mul_f32 v[120:121], v[64:65], v[96:97]
	v_add_f32_dpp v118, v118, v118 quad_perm:[1,0,3,2] row_mask:0xf bank_mask:0xf bound_ctrl:1
	v_pk_fma_f32 v[120:121], v[66:67], v[98:99], v[120:121]
	ds_read2st64_b32 v[116:117], v125 offset0:87 offset1:93
	v_add_f32_dpp v118, v118, v118 quad_perm:[2,3,0,1] row_mask:0xf bank_mask:0xf bound_ctrl:1
	v_add_f32_e32 v123, v120, v121
	ds_read_b128 v[88:91], v124 offset:22528
	v_add_f32_dpp v118, v118, v118 row_half_mirror row_mask:0xf bank_mask:0xf bound_ctrl:1
	ds_read_b128 v[84:87], v124 offset:22016
	ds_read_b128 v[80:83], v124 offset:21760
	v_add_f32_dpp v118, v118, v118 row_mirror row_mask:0xf bank_mask:0xf bound_ctrl:1
	v_pk_fma_f32 v[64:65], v[118:119], v[30:31], v[18:19] op_sel_hi:[0,1,1]
	v_pk_fma_f32 v[66:67], v[118:119], v[32:33], v[20:21] op_sel_hi:[0,1,1]
	ds_read_b128 v[92:95], v124 offset:22784
	ds_read_b128 v[76:79], v124 offset:21504
	ds_write2st64_b32 v128, v122, v123 offset0:40 offset1:44
	s_waitcnt lgkmcnt(7)
	v_pk_mul_f32 v[118:119], v[64:65], v[50:51]
	v_pk_mul_f32 v[46:47], v[46:47], v[62:63] op_sel:[0,1] op_sel_hi:[1,1]
	v_pk_fma_f32 v[118:119], v[66:67], v[52:53], v[118:119]
	v_pk_mul_f32 v[48:49], v[48:49], v[62:63] op_sel:[0,1] op_sel_hi:[1,1]
	v_pk_fma_f32 v[42:43], v[64:65], v[42:43], v[46:47]
	v_add_f32_e32 v118, v118, v119
	v_pk_fma_f32 v[44:45], v[66:67], v[44:45], v[48:49]
	v_pk_mul_f32 v[120:121], v[64:65], v[14:15]
	v_add_f32_dpp v118, v118, v118 quad_perm:[1,0,3,2] row_mask:0xf bank_mask:0xf bound_ctrl:1
	v_pk_fma_f32 v[120:121], v[66:67], v[16:17], v[120:121]
	ds_read_b128 v[108:111], v124 offset:24064
	v_add_f32_dpp v118, v118, v118 quad_perm:[2,3,0,1] row_mask:0xf bank_mask:0xf bound_ctrl:1
	v_add_f32_e32 v122, v120, v121
	ds_read_b128 v[104:107], v124 offset:23552
	v_add_f32_dpp v118, v118, v118 row_half_mirror row_mask:0xf bank_mask:0xf bound_ctrl:1
	ds_read_b128 v[100:103], v124 offset:23296
	ds_read_b128 v[112:115], v124 offset:24320
	v_add_f32_dpp v118, v118, v118 row_mirror row_mask:0xf bank_mask:0xf bound_ctrl:1
	v_pk_fma_f32 v[64:65], v[118:119], v[38:39], v[42:43] op_sel_hi:[0,1,1]
	v_pk_fma_f32 v[66:67], v[118:119], v[40:41], v[44:45] op_sel_hi:[0,1,1]
	ds_read_b128 v[96:99], v124 offset:23040
	s_waitcnt lgkmcnt(6)
	v_pk_mul_f32 v[118:119], v[64:65], v[88:89]
	v_pk_mul_f32 v[84:85], v[84:85], v[116:117] op_sel_hi:[1,0]
	v_pk_fma_f32 v[118:119], v[66:67], v[90:91], v[118:119]
	v_pk_mul_f32 v[86:87], v[86:87], v[116:117] op_sel_hi:[1,0]
	v_pk_fma_f32 v[80:81], v[64:65], v[80:81], v[84:85]
	v_add_f32_e32 v118, v118, v119
	v_pk_fma_f32 v[82:83], v[66:67], v[82:83], v[86:87]
	v_pk_mul_f32 v[120:121], v[64:65], v[34:35]
	v_add_f32_dpp v118, v118, v118 quad_perm:[1,0,3,2] row_mask:0xf bank_mask:0xf bound_ctrl:1
	v_pk_fma_f32 v[120:121], v[66:67], v[36:37], v[120:121]
	ds_read2st64_b32 v[62:63], v127 offset0:3 offset1:9
	v_add_f32_dpp v118, v118, v118 quad_perm:[2,3,0,1] row_mask:0xf bank_mask:0xf bound_ctrl:1
	v_add_f32_e32 v123, v120, v121
	ds_read_b128 v[26:29], v126 offset:1024
	v_add_f32_dpp v118, v118, v118 row_half_mirror row_mask:0xf bank_mask:0xf bound_ctrl:1
	ds_read_b128 v[22:25], v126 offset:512
	ds_read_b128 v[18:21], v126 offset:256
	v_add_f32_dpp v118, v118, v118 row_mirror row_mask:0xf bank_mask:0xf bound_ctrl:1
	v_pk_fma_f32 v[64:65], v[118:119], v[92:93], v[80:81] op_sel_hi:[0,1,1]
	v_pk_fma_f32 v[66:67], v[118:119], v[94:95], v[82:83] op_sel_hi:[0,1,1]
	ds_read_b128 v[30:33], v126 offset:1280
	ds_read_b128 v[14:17], v126
	ds_write2st64_b32 v128, v122, v123 offset0:48 offset1:52
	s_waitcnt lgkmcnt(7)
	v_pk_mul_f32 v[118:119], v[64:65], v[108:109]
	v_pk_mul_f32 v[104:105], v[104:105], v[116:117] op_sel:[0,1] op_sel_hi:[1,1]
	v_pk_fma_f32 v[118:119], v[66:67], v[110:111], v[118:119]
	v_pk_mul_f32 v[106:107], v[106:107], v[116:117] op_sel:[0,1] op_sel_hi:[1,1]
	v_pk_fma_f32 v[100:101], v[64:65], v[100:101], v[104:105]
	v_add_f32_e32 v118, v118, v119
	v_pk_fma_f32 v[102:103], v[66:67], v[102:103], v[106:107]
	v_pk_mul_f32 v[120:121], v[64:65], v[76:77]
	v_add_f32_dpp v118, v118, v118 quad_perm:[1,0,3,2] row_mask:0xf bank_mask:0xf bound_ctrl:1
	v_pk_fma_f32 v[120:121], v[66:67], v[78:79], v[120:121]
	ds_read_b128 v[50:53], v126 offset:2560
	v_add_f32_dpp v118, v118, v118 quad_perm:[2,3,0,1] row_mask:0xf bank_mask:0xf bound_ctrl:1
	v_add_f32_e32 v122, v120, v121
	ds_read_b128 v[46:49], v126 offset:2048
	v_add_f32_dpp v118, v118, v118 row_half_mirror row_mask:0xf bank_mask:0xf bound_ctrl:1
	ds_read_b128 v[42:45], v126 offset:1792
	ds_read_b128 v[38:41], v126 offset:2816
	v_add_f32_dpp v118, v118, v118 row_mirror row_mask:0xf bank_mask:0xf bound_ctrl:1
	v_pk_fma_f32 v[64:65], v[118:119], v[112:113], v[100:101] op_sel_hi:[0,1,1]
	v_pk_fma_f32 v[66:67], v[118:119], v[114:115], v[102:103] op_sel_hi:[0,1,1]
	ds_read_b128 v[34:37], v126 offset:1536
	v_pk_mul_f32 v[120:121], v[64:65], v[96:97]
	v_pk_fma_f32 v[120:121], v[66:67], v[98:99], v[120:121]
	v_add_f32_e32 v123, v120, v121
	ds_write2st64_b32 v128, v122, v123 offset0:56 offset1:60
	s_add_i32 s0, s10, 1
	s_cmp_lg_u32 s10, 2
	s_cselect_b32 s10, s0, 0
	s_add_i32 s22, s22, 1
	s_addk_i32 s21, 0x1000
	v_mov_b32_e32 v124, v126
	v_mov_b32_e32 v125, v127
	s_cmp_eq_u32 s10, 2
	s_movk_i32 s1, 0x6000
	s_cselect_b32 s0, 0xffff4000, s1
	v_add_u32_e32 v126, s0, v124
	v_add_u32_e32 v127, s0, v125
	v_xor_b32_e32 v128, 0x4000, v128
	s_cmpk_eq_u32 s22, 0x80
	s_waitcnt lgkmcnt(0)
	s_barrier
	s_cbranch_scc0 .Lsc_top
	s_branch .LBB0_508

; DI int tidx() { int t = threadIdx.x; asm volatile("" : "+v"(t)); return t; }
; __global__ void __launch_bounds__(512, 2) fwd_megakernel(Params p) {
;     ...
;       while (true) {
;         if (tidx() == 0) *s_item = atomicAdd(cnt, 1);
;         __syncthreads();
;         const int item = *s_item;
.LBB0_514:
	v_mov_b32_e32 v0, v201
	s_nop 0
	v_cmp_eq_u32_e32 vcc, 0, v0
	s_and_saveexec_b64 s[2:3], vcc
	s_cbranch_execz .LBB0_518
	v_cmp_eq_u32_e32 vcc, 1, v245
	s_nop 3
	s_cbranch_vccnz .Lq_have
	v_readlane_b32 s0, v252, 56
	v_readlane_b32 s1, v252, 57
	v_mov_b32_e32 v244, 1
	s_waitcnt vmcnt(0)
	s_nop 2
	global_atomic_add v243, v1, v244, s[0:1] sc0
.Lq_have:
	s_waitcnt vmcnt(0)
	v_mov_b32_e32 v245, 0
	v_readlane_b32 s0, v252, 49
	v_mov_b32_e32 v0, v243
	s_nop 0
	v_mov_b32_e32 v2, s0
	ds_write_b32 v2, v0

; #define MFMA32(a, b, c) __builtin_amdgcn_mfma_f32_32x32x16_bf16((a), (b), (c), 0, 0, 0)
; template <int MODE> ...
;     ...
;       for (int si = 0; si < 4; ++si) {
;         const bf16x8 fa = *(const bf16x8*)(Ks + (32 * kt + r31) * LDT + 16 * si + 8 * h);
;         s[kt] = MFMA32(fa, qf[si], s[kt]);
;       }
;     }
;     const bool selj = (MODE == 1) ? (((sel >> j) & 1) != 0) : true;
;     const bool interior = (MODE == 1) ? (64 * j + 63 <= qmin) : (MODE == 2) ? ((64 * j + 63 <= qmin) && (qmax - 64 * j < W)) : false;
.LBB0_525:
	v_add_u32_e32 v0, v147, v150
	ds_read_b128 v[2:5], v0
	ds_read_b128 v[18:21], v0 offset:32
	s_add_i32 s0, s2, 63
	s_cmp_gt_u32 s0, s23
	s_cselect_b64 s[6:7], -1, 0
	s_waitcnt lgkmcnt(1)
	v_mfma_f32_32x32x16_bf16 v[2:17], v[2:5], v[176:179], 0
	s_cmp_le_i32 s2, s3
	s_cselect_b64 s[12:13], -1, 0
	s_or_b64 s[38:39], s[6:7], s[12:13]
	s_mov_b64 s[36:37], -1
	s_and_b64 vcc, exec, s[38:39]
	s_waitcnt lgkmcnt(0)
	v_mfma_f32_32x32x16_bf16 v[2:17], v[18:21], v[180:183], v[2:17]
	ds_read_b128 v[18:21], v0 offset:64
	s_waitcnt lgkmcnt(0)
	v_mfma_f32_32x32x16_bf16 v[2:17], v[18:21], v[184:187], v[2:17]
	ds_read_b128 v[18:21], v0 offset:96
	s_waitcnt lgkmcnt(0)
	v_mfma_f32_32x32x16_bf16 v[2:17], v[18:21], v[188:191], v[2:17]
	ds_read_b128 v[18:21], v0 offset:4608
	s_waitcnt lgkmcnt(0)
	v_mfma_f32_32x32x16_bf16 v[64:79], v[18:21], v[176:179], 0
	ds_read_b128 v[18:21], v0 offset:4640
	s_waitcnt lgkmcnt(0)
	v_mfma_f32_32x32x16_bf16 v[64:79], v[18:21], v[180:183], v[64:79]
	ds_read_b128 v[18:21], v0 offset:4672
	s_waitcnt lgkmcnt(0)
	v_mfma_f32_32x32x16_bf16 v[64:79], v[18:21], v[184:187], v[64:79]
	ds_read_b128 v[18:21], v0 offset:4704
	s_waitcnt lgkmcnt(0)
	v_mfma_f32_32x32x16_bf16 v[64:79], v[18:21], v[188:191], v[64:79]
	v_mov_b32_e32 v19, v2
	s_nop 7
	s_cbranch_vccz .LBB0_527
; DI float xor32_max(float x) { auto r = __builtin_amdgcn_permlane32_swap(__float_as_uint(x), __float_as_uint(x), false, false); return fmaxf(__uint_as_float(r[0]), __uint_as_float(r[1])); }
; DI int crow(int i, int h) { return (i & 3) + 8 * (i >> 2) + 4 * h; }
; template <int MODE> ...
;     ...
;     } else {
; #pragma unroll
;       for (int kt = 0; kt < 2; ++kt)
; #pragma unroll
;         for (int e = 0; e < 16; ++e) {
;           const int key = 64 * j + 32 * kt + crow(e, h);
;           bool valid;
;           if (MODE == 0) valid = (16 * key + 31 <= qpos);
;           else if (MODE == 1) valid = selj && (key <= qpos);
;           else valid = (key <= qpos) && (qpos - key < W);
;           const float v = valid ? s[kt][e] : -1e30f;
;           s[kt][e] = v; mx = fmaxf(mx, v);
;         }
;     }
;     mx = xor32_max(mx);
	v_add_u32_e32 v0, s2, v148
	v_cmp_le_i32_e32 vcc, v0, v212
	v_cmp_gt_i32_e64 s[36:37], v0, v149
	s_and_b64 vcc, vcc, s[36:37]
	v_cndmask_b32_e32 v19, v229, v2, vcc
	v_cmp_lt_i32_e32 vcc, v0, v212
	v_cmp_ge_i32_e64 s[36:37], v0, v149
	s_and_b64 vcc, vcc, s[36:37]
	v_add_u32_e32 v20, 2, v0
	v_cndmask_b32_e32 v18, v229, v3, vcc
	v_cmp_le_i32_e32 vcc, v20, v212
	v_cmp_gt_i32_e64 s[36:37], v20, v149
	s_and_b64 vcc, vcc, s[36:37]
	v_add_u32_e32 v21, 3, v0
	v_cndmask_b32_e32 v20, v229, v4, vcc
	v_cmp_le_i32_e32 vcc, v21, v212
	v_cmp_gt_i32_e64 s[36:37], v21, v149
	s_mov_b32 s0, 0xf149f2ca
	s_and_b64 vcc, vcc, s[36:37]
	v_max3_f32 v22, v19, s0, v18
	v_cndmask_b32_e32 v21, v229, v5, vcc
	v_max3_f32 v24, v22, v20, v21
	v_add_u32_e32 v22, 8, v0
	v_cmp_le_i32_e32 vcc, v22, v212
	v_cmp_gt_i32_e64 s[36:37], v22, v149
	s_and_b64 vcc, vcc, s[36:37]
	v_add_u32_e32 v23, 9, v0
	v_cndmask_b32_e32 v22, v229, v6, vcc
	v_cmp_le_i32_e32 vcc, v23, v212
	v_cmp_gt_i32_e64 s[36:37], v23, v149
	s_and_b64 vcc, vcc, s[36:37]
	v_cndmask_b32_e32 v23, v229, v7, vcc
	v_max3_f32 v26, v24, v22, v23
	v_add_u32_e32 v24, 10, v0
	v_cmp_le_i32_e32 vcc, v24, v212
	v_cmp_gt_i32_e64 s[36:37], v24, v149
	s_and_b64 vcc, vcc, s[36:37]
	v_add_u32_e32 v25, 11, v0
	v_cndmask_b32_e32 v24, v229, v8, vcc
	v_cmp_le_i32_e32 vcc, v25, v212
	v_cmp_gt_i32_e64 s[36:37], v25, v149
	s_and_b64 vcc, vcc, s[36:37]
	v_cndmask_b32_e32 v25, v229, v9, vcc
	v_max3_f32 v28, v26, v24, v25
	v_add_u32_e32 v26, 16, v0
	v_cmp_le_i32_e32 vcc, v26, v212
	v_cmp_gt_i32_e64 s[36:37], v26, v149
	s_and_b64 vcc, vcc, s[36:37]
	v_add_u32_e32 v27, 17, v0
	v_cndmask_b32_e32 v26, v229, v10, vcc
	v_cmp_le_i32_e32 vcc, v27, v212
	v_cmp_gt_i32_e64 s[36:37], v27, v149
	s_and_b64 vcc, vcc, s[36:37]
	v_cndmask_b32_e32 v27, v229, v11, vcc
	v_max3_f32 v30, v28, v26, v27
	v_add_u32_e32 v28, 18, v0
	v_cmp_le_i32_e32 vcc, v28, v212
	v_cmp_gt_i32_e64 s[36:37], v28, v149
	s_and_b64 vcc, vcc, s[36:37]
	v_add_u32_e32 v29, 19, v0
	v_cndmask_b32_e32 v28, v229, v12, vcc
	v_cmp_le_i32_e32 vcc, v29, v212
	v_cmp_gt_i32_e64 s[36:37], v29, v149
	s_and_b64 vcc, vcc, s[36:37]
	v_cndmask_b32_e32 v29, v229, v13, vcc
	v_max3_f32 v81, v30, v28, v29
	v_add_u32_e32 v30, 24, v0
	v_cmp_le_i32_e32 vcc, v30, v212
	v_cmp_gt_i32_e64 s[36:37], v30, v149
	s_and_b64 vcc, vcc, s[36:37]
	v_add_u32_e32 v31, 25, v0
	v_cndmask_b32_e32 v30, v229, v14, vcc
	v_cmp_le_i32_e32 vcc, v31, v212
	v_cmp_gt_i32_e64 s[36:37], v31, v149
	s_and_b64 vcc, vcc, s[36:37]
	v_add_u32_e32 v82, 26, v0
	v_cndmask_b32_e32 v31, v229, v15, vcc
	v_cmp_le_i32_e32 vcc, v82, v212
	v_cmp_gt_i32_e64 s[36:37], v82, v149
	s_and_b64 vcc, vcc, s[36:37]
	v_add_u32_e32 v82, 27, v0
	v_cndmask_b32_e32 v155, v229, v16, vcc
	v_cmp_le_i32_e32 vcc, v82, v212
	v_cmp_gt_i32_e64 s[36:37], v82, v149
	s_and_b64 vcc, vcc, s[36:37]
	v_add_u32_e32 v82, 32, v0
	v_cndmask_b32_e32 v156, v229, v17, vcc
	v_cmp_le_i32_e32 vcc, v82, v212
	v_cmp_gt_i32_e64 s[36:37], v82, v149
	s_and_b64 vcc, vcc, s[36:37]
	v_add_u32_e32 v82, 33, v0
	v_cndmask_b32_e32 v153, v229, v64, vcc
	v_cmp_le_i32_e32 vcc, v82, v212
	v_cmp_gt_i32_e64 s[36:37], v82, v149
	s_and_b64 vcc, vcc, s[36:37]
	v_add_u32_e32 v82, 34, v0
	v_cndmask_b32_e32 v154, v229, v65, vcc
	v_cmp_le_i32_e32 vcc, v82, v212
	v_cmp_gt_i32_e64 s[36:37], v82, v149
	s_and_b64 vcc, vcc, s[36:37]
	v_add_u32_e32 v82, 35, v0
	v_cndmask_b32_e32 v157, v229, v66, vcc
	v_cmp_le_i32_e32 vcc, v82, v212
	v_cmp_gt_i32_e64 s[36:37], v82, v149
	s_and_b64 vcc, vcc, s[36:37]
	v_add_u32_e32 v82, 40, v0
	v_cndmask_b32_e32 v158, v229, v67, vcc
	v_cmp_le_i32_e32 vcc, v82, v212
	v_cmp_gt_i32_e64 s[36:37], v82, v149
	s_and_b64 vcc, vcc, s[36:37]
	v_add_u32_e32 v82, 41, v0
	v_cndmask_b32_e32 v160, v229, v68, vcc
	v_cmp_le_i32_e32 vcc, v82, v212
	v_cmp_gt_i32_e64 s[36:37], v82, v149
	s_and_b64 vcc, vcc, s[36:37]
	v_add_u32_e32 v82, 42, v0
	v_cndmask_b32_e32 v161, v229, v69, vcc
	v_cmp_le_i32_e32 vcc, v82, v212
	v_cmp_gt_i32_e64 s[36:37], v82, v149
	s_and_b64 vcc, vcc, s[36:37]
	v_add_u32_e32 v82, 43, v0
	v_cndmask_b32_e32 v164, v229, v70, vcc
	v_cmp_le_i32_e32 vcc, v82, v212
	v_cmp_gt_i32_e64 s[36:37], v82, v149
	s_and_b64 vcc, vcc, s[36:37]
	v_add_u32_e32 v82, 48, v0
	v_cndmask_b32_e32 v159, v229, v71, vcc
	v_cmp_le_i32_e32 vcc, v82, v212
	v_cmp_gt_i32_e64 s[36:37], v82, v149
	s_and_b64 vcc, vcc, s[36:37]
	v_add_u32_e32 v82, 49, v0
	v_cndmask_b32_e32 v162, v229, v72, vcc
	v_cmp_le_i32_e32 vcc, v82, v212
	v_cmp_gt_i32_e64 s[36:37], v82, v149
	s_and_b64 vcc, vcc, s[36:37]
	v_add_u32_e32 v82, 50, v0
	v_cndmask_b32_e32 v163, v229, v73, vcc
	v_cmp_le_i32_e32 vcc, v82, v212
	v_cmp_gt_i32_e64 s[36:37], v82, v149
	s_and_b64 vcc, vcc, s[36:37]
	v_add_u32_e32 v82, 51, v0
	v_cndmask_b32_e32 v165, v229, v74, vcc
	v_cmp_le_i32_e32 vcc, v82, v212
	v_cmp_gt_i32_e64 s[36:37], v82, v149
	s_and_b64 vcc, vcc, s[36:37]
	v_add_u32_e32 v82, 56, v0
	v_max3_f32 v81, v81, v30, v31
	v_cndmask_b32_e32 v166, v229, v75, vcc
	v_cmp_le_i32_e32 vcc, v82, v212
	v_cmp_gt_i32_e64 s[36:37], v82, v149
	v_max3_f32 v81, v81, v155, v156
	s_and_b64 vcc, vcc, s[36:37]
	v_add_u32_e32 v82, 57, v0
	v_max3_f32 v81, v81, v153, v154
	v_cndmask_b32_e32 v169, v229, v76, vcc
	v_cmp_le_i32_e32 vcc, v82, v212
	v_cmp_gt_i32_e64 s[36:37], v82, v149
	v_max3_f32 v81, v81, v157, v158
	s_and_b64 vcc, vcc, s[36:37]
	v_add_u32_e32 v82, 58, v0
	v_max3_f32 v81, v81, v160, v161
	v_cndmask_b32_e32 v170, v229, v77, vcc
	v_cmp_le_i32_e32 vcc, v82, v212
	v_cmp_gt_i32_e64 s[36:37], v82, v149
	v_max3_f32 v81, v81, v164, v159
	s_and_b64 vcc, vcc, s[36:37]
	v_add_u32_e32 v0, 59, v0
	v_max3_f32 v81, v81, v162, v163
	v_cndmask_b32_e32 v167, v229, v78, vcc
	v_cmp_le_i32_e32 vcc, v0, v212
	v_cmp_gt_i32_e64 s[36:37], v0, v149
	v_max3_f32 v81, v81, v165, v166
	s_and_b64 vcc, vcc, s[36:37]
	v_max3_f32 v81, v81, v169, v170
	v_cndmask_b32_e32 v168, v229, v79, vcc
	v_max3_f32 v0, v81, v167, v168
	s_mov_b64 s[36:37], 0

; template <int MODE> ...
;     ...
;     if (interior && (MODE == 2 || mnew > -1e29f)) {
; #pragma unroll
;       for (int kt = 0; kt < 2; ++kt)
; #pragma unroll
;         for (int e = 0; e < 16; ++e) {
;           const float pv = __builtin_amdgcn_exp2f(s[kt][e] - mnew);
;           l += pv; s[kt][e] = pv;
;         }
;     } else {
; #pragma unroll
;       for (int kt = 0; kt < 2; ++kt)
; #pragma unroll
;         for (int e = 0; e < 16; ++e) {
;           const float pv = (s[kt][e] > -1e29f) ? __builtin_amdgcn_exp2f(s[kt][e] - mnew) : 0.f;
;           l += pv; s[kt][e] = pv;
;         }
;     }
.LBB0_531:
	s_andn2_b64 vcc, exec, s[38:39]
	s_cbranch_vccnz .Lw_int
	v_sub_f32_e32 v3, v19, v2
	v_sub_f32_e32 v4, v18, v2
	v_sub_f32_e32 v5, v20, v2
	v_sub_f32_e32 v6, v21, v2
	v_sub_f32_e32 v7, v22, v2
	v_sub_f32_e32 v8, v23, v2
	v_sub_f32_e32 v9, v24, v2
	v_sub_f32_e32 v10, v25, v2
	v_sub_f32_e32 v11, v26, v2
	v_sub_f32_e32 v12, v27, v2
	v_sub_f32_e32 v13, v28, v2
	v_sub_f32_e32 v14, v29, v2
	v_sub_f32_e32 v15, v30, v2
	v_sub_f32_e32 v16, v31, v2
	v_sub_f32_e32 v17, v155, v2
	v_sub_f32_e32 v64, v156, v2
	v_sub_f32_e32 v65, v153, v2
	v_sub_f32_e32 v66, v154, v2
	v_sub_f32_e32 v67, v157, v2
	v_sub_f32_e32 v68, v158, v2
	v_sub_f32_e32 v69, v160, v2
	v_sub_f32_e32 v70, v161, v2
	v_sub_f32_e32 v71, v164, v2
	v_sub_f32_e32 v72, v159, v2
	v_sub_f32_e32 v73, v162, v2
	v_sub_f32_e32 v74, v163, v2
	v_sub_f32_e32 v75, v165, v2
	v_sub_f32_e32 v76, v166, v2
	v_sub_f32_e32 v77, v169, v2
	v_sub_f32_e32 v78, v170, v2
	v_sub_f32_e32 v79, v167, v2
	v_sub_f32_e32 v80, v168, v2
	v_exp_f32_e32 v96, v3
	v_exp_f32_e32 v97, v4
	v_exp_f32_e32 v98, v5
	v_exp_f32_e32 v99, v6
	v_exp_f32_e32 v100, v7
	v_exp_f32_e32 v101, v8
	v_exp_f32_e32 v102, v9
	v_exp_f32_e32 v103, v10
	v_exp_f32_e32 v104, v11
	v_exp_f32_e32 v105, v12
	v_exp_f32_e32 v106, v13
	v_exp_f32_e32 v107, v14
	v_exp_f32_e32 v108, v15
	v_exp_f32_e32 v109, v16
	v_exp_f32_e32 v110, v17
	v_exp_f32_e32 v111, v64
	v_exp_f32_e32 v112, v65
	v_exp_f32_e32 v113, v66
	v_exp_f32_e32 v114, v67
	v_exp_f32_e32 v115, v68
	v_exp_f32_e32 v116, v69
	v_exp_f32_e32 v117, v70
	v_exp_f32_e32 v118, v71
	v_exp_f32_e32 v119, v72
	v_exp_f32_e32 v120, v73
	v_exp_f32_e32 v121, v74
	v_exp_f32_e32 v122, v75
	v_exp_f32_e32 v123, v76
	v_exp_f32_e32 v124, v77
	v_exp_f32_e32 v125, v78
	v_exp_f32_e32 v126, v79
	v_exp_f32_e32 v127, v80
	v_mul_f32_e32 v0, v215, v0
	s_andn2_b64 vcc, exec, s[38:39]
	s_mov_b64 s[6:7], -1
	s_cbranch_vccnz .LBB0_533
	v_cmp_lt_f32_e32 vcc, s33, v19
	s_mov_b64 s[6:7], 0
	s_nop 0
	v_cndmask_b32_e32 v64, 0, v96, vcc
	v_cmp_lt_f32_e32 vcc, s33, v18
	v_add_f32_e32 v3, v64, v0
	s_nop 0
	v_cndmask_b32_e32 v65, 0, v97, vcc
	v_cmp_lt_f32_e32 vcc, s33, v20
	v_add_f32_e32 v3, v65, v3
	s_nop 0
	v_cndmask_b32_e32 v66, 0, v98, vcc
	v_cmp_lt_f32_e32 vcc, s33, v21
	v_add_f32_e32 v3, v66, v3
	s_nop 0
	v_cndmask_b32_e32 v67, 0, v99, vcc
	v_cmp_lt_f32_e32 vcc, s33, v22
	v_add_f32_e32 v3, v67, v3
	s_nop 0
	v_cndmask_b32_e32 v68, 0, v100, vcc
	v_cmp_lt_f32_e32 vcc, s33, v23
	v_add_f32_e32 v3, v68, v3
	s_nop 0
	v_cndmask_b32_e32 v69, 0, v101, vcc
	v_cmp_lt_f32_e32 vcc, s33, v24
	v_add_f32_e32 v3, v69, v3
	s_nop 0
	v_cndmask_b32_e32 v70, 0, v102, vcc
	v_cmp_lt_f32_e32 vcc, s33, v25
	v_add_f32_e32 v3, v70, v3
	s_nop 0
	v_cndmask_b32_e32 v71, 0, v103, vcc
	v_cmp_lt_f32_e32 vcc, s33, v26
	v_add_f32_e32 v3, v71, v3
	s_nop 0
	v_cndmask_b32_e32 v72, 0, v104, vcc
	v_cmp_lt_f32_e32 vcc, s33, v27
	v_add_f32_e32 v3, v72, v3
	s_nop 0
	v_cndmask_b32_e32 v73, 0, v105, vcc
	v_cmp_lt_f32_e32 vcc, s33, v28
	v_add_f32_e32 v3, v73, v3
	s_nop 0
	v_cndmask_b32_e32 v74, 0, v106, vcc
	v_cmp_lt_f32_e32 vcc, s33, v29
	v_add_f32_e32 v3, v74, v3
	s_nop 0
	v_cndmask_b32_e32 v75, 0, v107, vcc
	v_cmp_lt_f32_e32 vcc, s33, v30
	v_add_f32_e32 v3, v75, v3
	s_nop 0
	v_cndmask_b32_e32 v76, 0, v108, vcc
	v_cmp_lt_f32_e32 vcc, s33, v31
	v_add_f32_e32 v3, v76, v3
	s_nop 0
	v_cndmask_b32_e32 v77, 0, v109, vcc
	v_cmp_lt_f32_e32 vcc, s33, v155
	v_add_f32_e32 v3, v77, v3
	s_nop 0
	v_cndmask_b32_e32 v78, 0, v110, vcc
	v_cmp_lt_f32_e32 vcc, s33, v156
	v_add_f32_e32 v3, v78, v3
	s_nop 0
	v_cndmask_b32_e32 v79, 0, v111, vcc
	v_cmp_lt_f32_e32 vcc, s33, v153
	v_add_f32_e32 v3, v79, v3
	s_nop 0
	v_cndmask_b32_e32 v80, 0, v112, vcc
	v_cmp_lt_f32_e32 vcc, s33, v154
	v_add_f32_e32 v3, v80, v3
	s_nop 0
	v_cndmask_b32_e32 v81, 0, v113, vcc
	v_cmp_lt_f32_e32 vcc, s33, v157
	v_add_f32_e32 v3, v81, v3
	s_nop 0
	v_cndmask_b32_e32 v82, 0, v114, vcc
	v_cmp_lt_f32_e32 vcc, s33, v158
	v_add_f32_e32 v3, v82, v3
	s_nop 0
	v_cndmask_b32_e32 v83, 0, v115, vcc
	v_cmp_lt_f32_e32 vcc, s33, v160
	v_add_f32_e32 v3, v83, v3
	s_nop 0
	v_cndmask_b32_e32 v84, 0, v116, vcc
	v_cmp_lt_f32_e32 vcc, s33, v161
	v_add_f32_e32 v3, v84, v3
	s_nop 0
	v_cndmask_b32_e32 v85, 0, v117, vcc
	v_cmp_lt_f32_e32 vcc, s33, v164
	v_add_f32_e32 v3, v85, v3
	s_nop 0
	v_cndmask_b32_e32 v86, 0, v118, vcc
	v_cmp_lt_f32_e32 vcc, s33, v159
	v_add_f32_e32 v3, v86, v3
	s_nop 0
	v_cndmask_b32_e32 v87, 0, v119, vcc
	v_cmp_lt_f32_e32 vcc, s33, v162
	v_add_f32_e32 v3, v87, v3
	s_nop 0
	v_cndmask_b32_e32 v88, 0, v120, vcc
	v_cmp_lt_f32_e32 vcc, s33, v163
	v_add_f32_e32 v3, v88, v3
	s_nop 0
	v_cndmask_b32_e32 v89, 0, v121, vcc
	v_cmp_lt_f32_e32 vcc, s33, v165
	v_add_f32_e32 v3, v89, v3
	s_nop 0
	v_cndmask_b32_e32 v90, 0, v122, vcc
	v_cmp_lt_f32_e32 vcc, s33, v166
	v_add_f32_e32 v3, v90, v3
	s_nop 0
	v_cndmask_b32_e32 v91, 0, v123, vcc
	v_cmp_lt_f32_e32 vcc, s33, v169
	v_add_f32_e32 v3, v91, v3
	s_nop 0
	v_cndmask_b32_e32 v92, 0, v124, vcc
	v_cmp_lt_f32_e32 vcc, s33, v170
	v_add_f32_e32 v3, v92, v3
	s_nop 0
	v_cndmask_b32_e32 v93, 0, v125, vcc
	v_cmp_lt_f32_e32 vcc, s33, v167
	v_add_f32_e32 v3, v93, v3
	s_nop 0
	v_cndmask_b32_e32 v94, 0, v126, vcc
	v_cmp_lt_f32_e32 vcc, s33, v168
	v_add_f32_e32 v3, v94, v3
	s_nop 0
	v_cndmask_b32_e32 v95, 0, v127, vcc
	v_add_f32_e32 v215, v95, v3
; template <int MODE> ...
;     ...
;     if (interior && (MODE == 2 || mnew > -1e29f)) {
; #pragma unroll
;       for (int kt = 0; kt < 2; ++kt)
; #pragma unroll
;         for (int e = 0; e < 16; ++e) {
;           const float pv = __builtin_amdgcn_exp2f(s[kt][e] - mnew);
;           l += pv; s[kt][e] = pv;
;         }
.LBB0_533:
	s_andn2_b64 vcc, exec, s[6:7]
	s_cbranch_vccnz .LBB0_535
	v_add_f32_e32 v0, v96, v0
	v_add_f32_e32 v0, v97, v0
	v_add_f32_e32 v0, v98, v0
	v_add_f32_e32 v0, v99, v0
	v_add_f32_e32 v0, v100, v0
	v_add_f32_e32 v0, v101, v0
	v_add_f32_e32 v0, v102, v0
	v_add_f32_e32 v0, v103, v0
	v_add_f32_e32 v0, v104, v0
	v_add_f32_e32 v0, v105, v0
	v_add_f32_e32 v0, v106, v0
	v_add_f32_e32 v0, v107, v0
	v_add_f32_e32 v0, v108, v0
	v_add_f32_e32 v0, v109, v0
	v_add_f32_e32 v0, v110, v0
	v_add_f32_e32 v0, v111, v0
	v_add_f32_e32 v0, v112, v0
	v_add_f32_e32 v0, v113, v0
	v_add_f32_e32 v0, v114, v0
	v_add_f32_e32 v0, v115, v0
	v_add_f32_e32 v0, v116, v0
	v_add_f32_e32 v0, v117, v0
	v_add_f32_e32 v0, v118, v0
	v_add_f32_e32 v0, v119, v0
	v_add_f32_e32 v0, v120, v0
	v_add_f32_e32 v0, v121, v0
	v_add_f32_e32 v0, v122, v0
	v_add_f32_e32 v0, v123, v0
	v_add_f32_e32 v0, v124, v0
	v_add_f32_e32 v0, v125, v0
	v_add_f32_e32 v0, v126, v0
	v_mov_b64_e32 v[64:65], v[96:97]
	v_add_f32_e32 v215, v127, v0
	v_mov_b64_e32 v[66:67], v[98:99]
	v_mov_b64_e32 v[68:69], v[100:101]
	v_mov_b64_e32 v[70:71], v[102:103]
	v_mov_b64_e32 v[72:73], v[104:105]
	v_mov_b64_e32 v[74:75], v[106:107]
	v_mov_b64_e32 v[76:77], v[108:109]
	v_mov_b64_e32 v[78:79], v[110:111]
	v_mov_b64_e32 v[80:81], v[112:113]
	v_mov_b64_e32 v[82:83], v[114:115]
	v_mov_b64_e32 v[84:85], v[116:117]
	v_mov_b64_e32 v[86:87], v[118:119]
	v_mov_b64_e32 v[88:89], v[120:121]
	v_mov_b64_e32 v[90:91], v[122:123]
	v_mov_b64_e32 v[92:93], v[124:125]
	v_mov_b64_e32 v[94:95], v[126:127]
	s_branch .LBB0_535
.Lw_int:
	v_sub_f32_e32 v19, v19, v2
	v_sub_f32_e32 v3, v3, v2
	v_sub_f32_e32 v4, v4, v2
	v_sub_f32_e32 v5, v5, v2
	v_sub_f32_e32 v6, v6, v2
	v_sub_f32_e32 v7, v7, v2
	v_sub_f32_e32 v8, v8, v2
	v_sub_f32_e32 v9, v9, v2
	v_sub_f32_e32 v10, v10, v2
	v_sub_f32_e32 v11, v11, v2
	v_sub_f32_e32 v12, v12, v2
	v_sub_f32_e32 v13, v13, v2
	v_sub_f32_e32 v14, v14, v2
	v_sub_f32_e32 v15, v15, v2
	v_sub_f32_e32 v16, v16, v2
	v_sub_f32_e32 v17, v17, v2
	v_sub_f32_e32 v64, v64, v2
	v_sub_f32_e32 v65, v65, v2
	v_sub_f32_e32 v66, v66, v2
	v_sub_f32_e32 v67, v67, v2
	v_sub_f32_e32 v68, v68, v2
	v_sub_f32_e32 v69, v69, v2
	v_sub_f32_e32 v70, v70, v2
	v_sub_f32_e32 v71, v71, v2
	v_sub_f32_e32 v72, v72, v2
	v_sub_f32_e32 v73, v73, v2
	v_sub_f32_e32 v74, v74, v2
	v_sub_f32_e32 v75, v75, v2
	v_sub_f32_e32 v76, v76, v2
	v_sub_f32_e32 v77, v77, v2
	v_sub_f32_e32 v78, v78, v2
	v_sub_f32_e32 v79, v79, v2
	v_exp_f32_e32 v80, v64
	v_exp_f32_e32 v81, v65
	v_exp_f32_e32 v82, v66
	v_exp_f32_e32 v83, v67
	v_exp_f32_e32 v84, v68
	v_exp_f32_e32 v85, v69
	v_exp_f32_e32 v86, v70
	v_exp_f32_e32 v87, v71
	v_exp_f32_e32 v88, v72
	v_exp_f32_e32 v89, v73
	v_exp_f32_e32 v90, v74
	v_exp_f32_e32 v91, v75
	v_exp_f32_e32 v92, v76
	v_exp_f32_e32 v93, v77
	v_exp_f32_e32 v94, v78
	v_exp_f32_e32 v95, v79
	v_exp_f32_e32 v64, v19
	v_exp_f32_e32 v65, v3
	v_exp_f32_e32 v66, v4
	v_exp_f32_e32 v67, v5
	v_exp_f32_e32 v68, v6
	v_exp_f32_e32 v69, v7
	v_exp_f32_e32 v70, v8
	v_exp_f32_e32 v71, v9
	v_exp_f32_e32 v72, v10
	v_exp_f32_e32 v73, v11
	v_exp_f32_e32 v74, v12
	v_exp_f32_e32 v75, v13
	v_exp_f32_e32 v76, v14
	v_exp_f32_e32 v77, v15
	v_exp_f32_e32 v78, v16
	v_exp_f32_e32 v79, v17
	v_mul_f32_e32 v0, v215, v0
	v_add_f32_e32 v0, v64, v0
	v_add_f32_e32 v0, v65, v0
	v_add_f32_e32 v0, v66, v0
	v_add_f32_e32 v0, v67, v0
	v_add_f32_e32 v0, v68, v0
	v_add_f32_e32 v0, v69, v0
	v_add_f32_e32 v0, v70, v0
	v_add_f32_e32 v0, v71, v0
	v_add_f32_e32 v0, v72, v0
	v_add_f32_e32 v0, v73, v0
	v_add_f32_e32 v0, v74, v0
	v_add_f32_e32 v0, v75, v0
	v_add_f32_e32 v0, v76, v0
	v_add_f32_e32 v0, v77, v0
	v_add_f32_e32 v0, v78, v0
	v_add_f32_e32 v0, v79, v0
	v_add_f32_e32 v0, v80, v0
	v_add_f32_e32 v0, v81, v0
	v_add_f32_e32 v0, v82, v0
	v_add_f32_e32 v0, v83, v0
	v_add_f32_e32 v0, v84, v0
	v_add_f32_e32 v0, v85, v0
	v_add_f32_e32 v0, v86, v0
	v_add_f32_e32 v0, v87, v0
	v_add_f32_e32 v0, v88, v0
	v_add_f32_e32 v0, v89, v0
	v_add_f32_e32 v0, v90, v0
	v_add_f32_e32 v0, v91, v0
	v_add_f32_e32 v0, v92, v0
	v_add_f32_e32 v0, v93, v0
	v_add_f32_e32 v0, v94, v0
	v_add_f32_e32 v215, v95, v0

; DI unsigned pack2(float a, float b) { fv2 v = {a, b}; return __builtin_bit_cast(unsigned, __builtin_convertvector(v, bfv2)); }
; template <int MODE> ...
;     ...
;     } else {
; #pragma unroll
;       for (int kt = 0; kt < 2; ++kt)
; #pragma unroll
;         for (int e = 0; e < 16; ++e) {
;           const float pv = (s[kt][e] > -1e29f) ? __builtin_amdgcn_exp2f(s[kt][e] - mnew) : 0.f;
;           l += pv; s[kt][e] = pv;
;         }
;     }
;     if (MODE == 0) {
;       if (impw != nullptr) {
; #pragma unroll
;         for (int kt = 0; kt < 2; ++kt)
; #pragma unroll
;           for (int q = 0; q < 4; ++q) {
;             impw[16 * j + 8 * kt + 2 * q + h] = (s[kt][4 * q] + s[kt][4 * q + 1]) + (s[kt][4 * q + 2] + s[kt][4 * q + 3]);
;             lastb[(j * 8 + kt * 4 + q) * 512 + tid] = s[kt][4 * q + 3];
;           }
;         mts[j * 512 + tid] = mnew;
;       }
;     }
; #pragma unroll
;     for (int kt = 0; kt < 2; ++kt)
; #pragma unroll
;       for (int sp = 0; sp < 2; ++sp) {
;         const bf16x8 fb = __builtin_bit_cast(bf16x8, make_uint4(pack2(s[kt][8 * sp + 0], s[kt][8 * sp + 1]), pack2(s[kt][8 * sp + 2], s[kt][8 * sp + 3]),
;                                                                pack2(s[kt][8 * sp + 4], s[kt][8 * sp + 5]), pack2(s[kt][8 * sp + 6], s[kt][8 * sp + 7])));
.LBB0_562:
	v_sub_f32_e32 v5, v137, v2
	v_exp_f32_e32 v5, v5
	v_sub_f32_e32 v8, v139, v2
	v_exp_f32_e32 v8, v8
	v_sub_f32_e32 v10, v138, v2
	v_exp_f32_e32 v10, v10
	v_sub_f32_e32 v11, v136, v2
	v_cmp_lt_f32_e32 vcc, s33, v137
	v_exp_f32_e32 v11, v11
	s_addk_i32 s2, 0x400
	v_cndmask_b32_e32 v5, 0, v5, vcc
	v_cmp_lt_f32_e32 vcc, s33, v139
	v_fma_f32 v0, v134, v0, v5
	s_cmpk_eq_i32 s2, 0x800
	v_cndmask_b32_e32 v8, 0, v8, vcc
	v_cmp_lt_f32_e32 vcc, s33, v138
	v_add_f32_e32 v0, v8, v0
	s_nop 0
	v_cndmask_b32_e32 v10, 0, v10, vcc
	v_cmp_lt_f32_e32 vcc, s33, v136
	v_add_f32_e32 v0, v10, v0
	s_nop 0
	v_cndmask_b32_e32 v14, 0, v11, vcc
	v_sub_f32_e32 v11, v99, v2
	v_exp_f32_e32 v11, v11
	v_cmp_lt_f32_e32 vcc, s33, v99
	v_add_f32_e32 v0, v14, v0
	s_nop 0
	v_cndmask_b32_e32 v15, 0, v11, vcc
	v_sub_f32_e32 v11, v21, v2
	v_exp_f32_e32 v11, v11
	v_cmp_lt_f32_e32 vcc, s33, v21
	v_add_f32_e32 v0, v15, v0
	s_nop 0
	v_cndmask_b32_e32 v21, 0, v11, vcc
	v_sub_f32_e32 v11, v23, v2
	v_exp_f32_e32 v11, v11
	v_cmp_lt_f32_e32 vcc, s33, v23
	v_add_f32_e32 v0, v21, v0
	s_nop 0
	v_cndmask_b32_e32 v23, 0, v11, vcc
	v_sub_f32_e32 v11, v27, v2
	v_exp_f32_e32 v11, v11
	v_cmp_lt_f32_e32 vcc, s33, v27
	v_add_f32_e32 v0, v23, v0
	s_nop 0
	v_cndmask_b32_e32 v27, 0, v11, vcc
	v_add_f32_e32 v11, v27, v0
	v_sub_f32_e32 v0, v24, v2
	v_exp_f32_e32 v0, v0
	v_cmp_lt_f32_e32 vcc, s33, v24
	s_nop 1
	v_cndmask_b32_e32 v0, 0, v0, vcc
	v_add_f32_e32 v13, v0, v11
	v_sub_f32_e32 v11, v103, v2
	v_exp_f32_e32 v11, v11
	v_cmp_lt_f32_e32 vcc, s33, v103
	s_nop 1
	v_cndmask_b32_e32 v11, 0, v11, vcc
	v_add_f32_e32 v16, v11, v13
	v_sub_f32_e32 v13, v102, v2
	v_exp_f32_e32 v13, v13
	v_cmp_lt_f32_e32 vcc, s33, v102
	s_nop 1
	v_cndmask_b32_e32 v13, 0, v13, vcc
	v_add_f32_e32 v17, v13, v16
	v_sub_f32_e32 v16, v101, v2
	v_exp_f32_e32 v16, v16
	v_cmp_lt_f32_e32 vcc, s33, v101
	s_nop 1
	v_cndmask_b32_e32 v16, 0, v16, vcc
	v_add_f32_e32 v24, v16, v17
	v_sub_f32_e32 v17, v100, v2
	v_exp_f32_e32 v17, v17
	v_cmp_lt_f32_e32 vcc, s33, v100
	s_nop 1
	v_cndmask_b32_e32 v17, 0, v17, vcc
	v_add_f32_e32 v99, v17, v24
	v_sub_f32_e32 v24, v98, v2
	v_exp_f32_e32 v24, v24
	v_cmp_lt_f32_e32 vcc, s33, v98
	s_nop 1
	v_cndmask_b32_e32 v24, 0, v24, vcc
	v_cmp_lt_f32_e32 vcc, s33, v26
	v_sub_f32_e32 v26, v26, v2
	v_exp_f32_e32 v26, v26
	v_add_f32_e32 v98, v24, v99
	v_cndmask_b32_e32 v26, 0, v26, vcc
	v_cmp_lt_f32_e32 vcc, s33, v30
	v_sub_f32_e32 v30, v30, v2
	v_exp_f32_e32 v30, v30
	v_add_f32_e32 v98, v26, v98
	v_cndmask_b32_e32 v30, 0, v30, vcc
	v_cmp_lt_f32_e32 vcc, s33, v29
	v_sub_f32_e32 v29, v29, v2
	v_exp_f32_e32 v29, v29
	v_add_f32_e32 v98, v30, v98
	v_cndmask_b32_e32 v29, 0, v29, vcc
	v_cmp_lt_f32_e32 vcc, s33, v97
	v_sub_f32_e32 v97, v97, v2
	v_exp_f32_e32 v97, v97
	v_add_f32_e32 v98, v29, v98
	v_cndmask_b32_e32 v97, 0, v97, vcc
	v_cmp_lt_f32_e32 vcc, s33, v96
	v_sub_f32_e32 v96, v96, v2
	v_exp_f32_e32 v96, v96
	v_add_f32_e32 v98, v97, v98
	v_cndmask_b32_e32 v96, 0, v96, vcc
	v_cmp_lt_f32_e32 vcc, s33, v31
	v_sub_f32_e32 v31, v31, v2
	v_exp_f32_e32 v31, v31
	v_add_f32_e32 v98, v96, v98
	v_cndmask_b32_e32 v31, 0, v31, vcc
	v_cmp_lt_f32_e32 vcc, s33, v28
	v_sub_f32_e32 v28, v28, v2
	v_exp_f32_e32 v28, v28
	v_add_f32_e32 v98, v31, v98
	v_cndmask_b32_e32 v28, 0, v28, vcc
	v_cmp_lt_f32_e32 vcc, s33, v25
	v_sub_f32_e32 v25, v25, v2
	v_exp_f32_e32 v25, v25
	v_add_f32_e32 v98, v28, v98
	v_cndmask_b32_e32 v25, 0, v25, vcc
	v_cmp_lt_f32_e32 vcc, s33, v22
	v_sub_f32_e32 v22, v22, v2
	v_exp_f32_e32 v22, v22
	v_add_f32_e32 v98, v25, v98
	v_cndmask_b32_e32 v22, 0, v22, vcc
	v_cmp_lt_f32_e32 vcc, s33, v20
	v_sub_f32_e32 v20, v20, v2
	v_exp_f32_e32 v20, v20
	v_add_f32_e32 v98, v22, v98
	v_cndmask_b32_e32 v102, 0, v20, vcc
	v_cmp_lt_f32_e32 vcc, s33, v19
	v_sub_f32_e32 v19, v19, v2
	v_exp_f32_e32 v19, v19
	v_add_f32_e32 v20, v102, v98
	v_cndmask_b32_e32 v103, 0, v19, vcc
	v_cmp_lt_f32_e32 vcc, s33, v18
	v_sub_f32_e32 v18, v18, v2
	v_exp_f32_e32 v18, v18
	v_add_f32_e32 v19, v103, v20
	v_cndmask_b32_e32 v104, 0, v18, vcc
	v_cmp_lt_f32_e32 vcc, s33, v12
	v_sub_f32_e32 v12, v12, v2
	v_exp_f32_e32 v12, v12
	v_add_f32_e32 v18, v104, v19
	v_cndmask_b32_e32 v12, 0, v12, vcc
	v_cmp_lt_f32_e32 vcc, s33, v9
	v_sub_f32_e32 v9, v9, v2
	v_exp_f32_e32 v9, v9
	v_add_f32_e32 v18, v12, v18
	v_cndmask_b32_e32 v105, 0, v9, vcc
	v_cmp_lt_f32_e32 vcc, s33, v7
	v_sub_f32_e32 v7, v7, v2
	v_exp_f32_e32 v7, v7
	v_add_f32_e32 v9, v105, v18
	v_cndmask_b32_e32 v106, 0, v7, vcc
	v_cmp_lt_f32_e32 vcc, s33, v6
	v_sub_f32_e32 v6, v6, v2
	v_exp_f32_e32 v6, v6
	v_add_f32_e32 v7, v106, v9
	v_add_f32_e32 v9, v23, v27
	v_cndmask_b32_e32 v107, 0, v6, vcc
	v_cmp_lt_f32_e32 vcc, s33, v4
	v_sub_f32_e32 v4, v4, v2
	v_exp_f32_e32 v4, v4
	v_add_f32_e32 v6, v107, v7
	v_add_f32_e32 v7, v15, v21
	v_add_f32_e32 v7, v7, v9
	v_cndmask_b32_e32 v108, 0, v4, vcc
	v_cmp_lt_f32_e32 vcc, s33, v3
	v_sub_f32_e32 v3, v3, v2
	v_exp_f32_e32 v3, v3
	v_add_f32_e32 v4, v108, v6
	v_add_f32_e32 v6, v10, v14
	v_add_f32_e32 v9, v13, v16
	v_cndmask_b32_e32 v3, 0, v3, vcc
	v_add_f32_e32 v134, v3, v4
	v_add_f32_e32 v4, v5, v8
	v_add_f32_e32 v4, v4, v6
	v_add_u32_e32 v6, 0, v132
	ds_write_b32 v6, v4
	v_add_u32_e32 v4, 0, v130
	ds_write_b32 v4, v14 offset:61440
	ds_write_b32 v6, v7 offset:8
	ds_write_b32 v4, v27 offset:63488
	v_add_f32_e32 v7, v0, v11
	v_add_f32_e32 v7, v7, v9
	ds_write_b32 v6, v7 offset:16
	v_add_u32_e32 v7, 0x10000, v4
	ds_write_b32 v7, v16
	v_add_f32_e32 v7, v17, v24
	v_add_f32_e32 v9, v26, v30
	v_add_f32_e32 v7, v7, v9
	ds_write_b32 v6, v7 offset:24
	v_add_u32_e32 v7, 0x10800, v4
	ds_write_b32 v7, v30
	v_add_f32_e32 v7, v29, v97
	v_add_f32_e32 v9, v96, v31
	v_add_f32_e32 v7, v7, v9
	ds_write_b32 v6, v7 offset:32
	v_add_u32_e32 v7, 0x11000, v4
	ds_write_b32 v7, v31
	v_add_f32_e32 v7, v28, v25
	v_add_f32_e32 v9, v22, v102
	v_add_f32_e32 v7, v7, v9
	ds_write_b32 v6, v7 offset:40
	v_add_u32_e32 v7, 0x11800, v4
	ds_write_b32 v7, v102
	v_add_f32_e32 v7, v103, v104
	v_add_f32_e32 v9, v12, v105
	v_add_f32_e32 v7, v7, v9
	ds_write_b32 v6, v7 offset:48
	v_add_u32_e32 v7, 0x12000, v4
	ds_write_b32 v7, v105
	v_add_f32_e32 v7, v106, v107
	v_add_f32_e32 v9, v108, v3
	v_add_f32_e32 v7, v7, v9
	v_add_u32_e32 v4, 0x12800, v4
	ds_write_b32 v6, v7 offset:56
	ds_write_b32 v4, v3
	v_add_u32_e32 v4, 0, v131
	ds_write_b32 v4, v2
	v_cvt_pk_bf16_f32 v4, v5, v8
	v_cvt_pk_bf16_f32 v5, v10, v14
	v_add_u32_e32 v14, 0x2000, v133
	v_cvt_pk_bf16_f32 v6, v15, v21
	ds_read2_b64 v[18:21], v14 offset0:128 offset1:130
	ds_read2_b64 v[98:101], v14 offset0:132 offset1:134
	v_cvt_pk_bf16_f32 v7, v23, v27
	v_add_u32_e32 v15, 0x3000, v133
	v_add_u32_e32 v131, 0x800, v131
	s_waitcnt lgkmcnt(1)
; #define MFMA32(a, b, c) __builtin_amdgcn_mfma_f32_32x32x16_bf16((a), (b), (c), 0, 0, 0)
; DI unsigned pack2(float a, float b) { fv2 v = {a, b}; return __builtin_bit_cast(unsigned, __builtin_convertvector(v, bfv2)); }
; template <int MODE> ...
;     ...
; #pragma unroll
;     for (int kt = 0; kt < 2; ++kt)
; #pragma unroll
;       for (int sp = 0; sp < 2; ++sp) {
;         const bf16x8 fb = __builtin_bit_cast(bf16x8, make_uint4(pack2(s[kt][8 * sp + 0], s[kt][8 * sp + 1]), pack2(s[kt][8 * sp + 2], s[kt][8 * sp + 3]),
;                                                                pack2(s[kt][8 * sp + 4], s[kt][8 * sp + 5]), pack2(s[kt][8 * sp + 6], s[kt][8 * sp + 7])));
; #pragma unroll
;         for (int dt = 0; dt < 2; ++dt) {
;           const bf16_t* vr = Vs + (32 * dt + r31) * LDT + 32 * kt + 16 * sp + 4 * h;
;           const uint2 lo = *(const uint2*)vr; const uint2 hi = *(const uint2*)(vr + 8);
;           const bf16x8 fa = __builtin_bit_cast(bf16x8, make_uint4(lo.x, lo.y, hi.x, hi.y));
;           o[dt] = MFMA32(fa, fb, o[dt]);
;         }
;       }
	v_mfma_f32_32x32x16_bf16 v[64:79], v[18:21], v[4:7], v[64:79]
	ds_read2_b64 v[18:21], v15 offset0:192 offset1:194
	v_add_u32_e32 v132, 64, v132
	v_add_u32_e32 v130, 0x4000, v130
	s_waitcnt lgkmcnt(0)
	v_mfma_f32_32x32x16_bf16 v[80:95], v[18:21], v[4:7], v[80:95]
	v_cvt_pk_bf16_f32 v4, v0, v11
	ds_read2_b64 v[8:11], v15 offset0:196 offset1:198
	v_cvt_pk_bf16_f32 v5, v13, v16
	v_cvt_pk_bf16_f32 v6, v17, v24
	v_cvt_pk_bf16_f32 v7, v26, v30
	s_waitcnt lgkmcnt(0)
	s_nop 0
	v_mfma_f32_32x32x16_bf16 v[80:95], v[8:11], v[4:7], v[80:95]
	ds_read2_b64 v[8:11], v14 offset0:136 offset1:138
	v_mfma_f32_32x32x16_bf16 v[64:79], v[98:101], v[4:7], v[64:79]
	v_cvt_pk_bf16_f32 v4, v29, v97
	v_cvt_pk_bf16_f32 v5, v96, v31
	v_cvt_pk_bf16_f32 v6, v28, v25
	v_cvt_pk_bf16_f32 v7, v22, v102
	s_waitcnt lgkmcnt(0)
	s_nop 0
	v_mfma_f32_32x32x16_bf16 v[64:79], v[8:11], v[4:7], v[64:79]
	ds_read2_b64 v[8:11], v15 offset0:200 offset1:202
	s_waitcnt lgkmcnt(0)
	v_mfma_f32_32x32x16_bf16 v[80:95], v[8:11], v[4:7], v[80:95]
	ds_read2_b64 v[8:11], v14 offset0:140 offset1:142
	v_cvt_pk_bf16_f32 v4, v103, v104
	v_cvt_pk_bf16_f32 v5, v12, v105
	v_cvt_pk_bf16_f32 v6, v106, v107
	v_cvt_pk_bf16_f32 v7, v108, v3
	s_waitcnt lgkmcnt(0)
	s_nop 0
	v_mfma_f32_32x32x16_bf16 v[64:79], v[8:11], v[4:7], v[64:79]
	ds_read2_b64 v[8:11], v15 offset0:204 offset1:206
	s_waitcnt lgkmcnt(0)
	v_mfma_f32_32x32x16_bf16 v[80:95], v[8:11], v[4:7], v[80:95]
	s_cbranch_scc1 .LBB0_564
	v_mov_b32_e32 v135, v2
	s_branch .LBB0_558
.Ltramp_1087:
	s_branch .LBB0_1087

; DI float xor32_sum(float x) { auto r = __builtin_amdgcn_permlane32_swap(__float_as_uint(x), __float_as_uint(x), false, false); return __uint_as_float(r[0]) + __uint_as_float(r[1]); }
; DI void nsa_item(const Params& p, int l_, int item, char* smraw, bool wr = true) {
;     ...
;   lt = xor32_sum(l);
;   inv = (lt > 0.f) ? 1.f / lt : 0.f;
; #pragma unroll
;   for (int e = 0; e < 16; ++e) { ot[0][e] += g0 * inv * o[0][e]; ot[1][e] += g0 * inv * o[1][e]; }
;   unsigned sel, uni;
;   if (cur < 16) {
;     sel = (1u << (cur + 1)) - 1u; uni = sel;
;   } else {
;     {
;       const float f0 = __builtin_amdgcn_exp2f(mts[tid] - m) * inv, f1 = __builtin_amdgcn_exp2f(mts[512 + tid] - m) * inv;
; #pragma unroll
;       for (int jt = 0; jt < 2; ++jt)
; #pragma unroll
;         for (int kt = 0; kt < 2; ++kt)
; #pragma unroll
;           for (int q = 0; q < 4; ++q) impw[16 * jt + 8 * kt + 2 * q + h] *= (jt ? f1 : f0);
;       __syncthreads();
; #pragma unroll
;       for (int jt = 0; jt < 2; ++jt)
; #pragma unroll
;         for (int kt = 0; kt < 2; ++kt)
; #pragma unroll
;           for (int q = 0; q < 4; ++q) {
;             const int j1 = 16 * jt + 8 * kt + 2 * q + h + 1;
;             if (j1 < 32) impw[j1] += lastb[(jt * 8 + kt * 4 + q) * 512 + tid] * (jt ? f1 : f0);
.Ltramp_19:
	s_branch .LBB0_19
.LBB0_564:
	s_waitcnt vmcnt(0)
	v_mov_b32_e32 v0, v134
	s_nop 1
	v_permlane32_swap_b32_e32 v134, v0
	v_add_f32_e32 v0, v134, v0
	v_div_scale_f32 v3, s[2:3], v0, v0, 1.0
	v_rcp_f32_e32 v4, v3
	s_cmp_gt_u32 s22, 15
	v_writelane_b32 v251, s20, 6
	v_cmp_lt_f32_e64 s[36:37], 0, v0
	v_fma_f32 v5, -v3, v4, 1.0
	v_fmac_f32_e32 v4, v5, v4
	v_div_scale_f32 v5, vcc, 1.0, v0, 1.0
	v_mul_f32_e32 v6, v5, v4
	v_fma_f32 v7, -v3, v6, v5
	v_fmac_f32_e32 v6, v7, v4
	v_fma_f32 v3, -v3, v6, v5
	v_div_fmas_f32 v3, v3, v4, v6
	v_div_fixup_f32 v0, v3, v0, 1.0
	s_cselect_b64 s[0:1], -1, 0
	v_cndmask_b32_e64 v235, 0, v0, s[36:37]
	s_mov_b64 s[4:5], -1
	v_writelane_b32 v251, s0, 7
	s_and_b64 vcc, exec, s[0:1]
	v_readfirstlane_b32 s20, v0
	v_writelane_b32 v251, s1, 8
	s_cbranch_vccz .LBB0_590
	v_lshl_add_u32 v3, v143, 2, 0
	v_add_u32_e32 v0, 0x17000, v3
	ds_read2st64_b32 v[4:5], v0 offset1:8
	v_or_b32_e32 v0, v125, v140
	s_movk_i32 s0, 0x84
	v_mul_lo_u32 v0, v0, s0
	v_add_u32_e32 v0, 0, v0
	s_waitcnt lgkmcnt(0)
	v_sub_f32_e32 v4, v4, v2
	v_exp_f32_e32 v4, v4
	v_lshl_add_u32 v12, v230, 2, v0
	v_add_u32_e32 v13, 0x4800, v12
	v_sub_f32_e32 v2, v5, v2
	v_mul_f32_e32 v14, v235, v4
	ds_read2_b32 v[4:5], v13 offset1:2
	ds_read2_b32 v[6:7], v13 offset0:4 offset1:6
	ds_read2_b32 v[8:9], v13 offset0:8 offset1:10
	ds_read2_b32 v[10:11], v13 offset0:12 offset1:14
	v_exp_f32_e32 v2, v2
	v_cmp_eq_u32_e32 vcc, 0, v230
	s_waitcnt lgkmcnt(3)
	v_mul_f32_e32 v4, v4, v14
	v_mul_f32_e32 v5, v14, v5
	ds_write2_b32 v13, v4, v5 offset1:2
	s_waitcnt lgkmcnt(3)
	v_mul_f32_e32 v4, v14, v6
	v_mul_f32_e32 v5, v14, v7
	ds_write2_b32 v13, v4, v5 offset0:4 offset1:6
	s_waitcnt lgkmcnt(3)
	v_mul_f32_e32 v4, v14, v8
	v_mul_f32_e32 v5, v14, v9
	ds_write2_b32 v13, v4, v5 offset0:8 offset1:10
	ds_read2_b32 v[4:5], v13 offset0:16 offset1:18
	s_waitcnt lgkmcnt(4)
	v_mul_f32_e32 v6, v14, v10
	v_mul_f32_e32 v7, v14, v11
	ds_write2_b32 v13, v6, v7 offset0:12 offset1:14
	ds_read2_b32 v[6:7], v13 offset0:20 offset1:22
	v_mul_f32_e32 v2, v235, v2
	s_waitcnt lgkmcnt(2)
	v_mul_f32_e32 v4, v2, v4
	v_mul_f32_e32 v5, v2, v5
	ds_write2_b32 v13, v4, v5 offset0:16 offset1:18
	ds_read2_b32 v[4:5], v13 offset0:24 offset1:26
	s_waitcnt lgkmcnt(2)
	v_mul_f32_e32 v8, v2, v6
	v_mul_f32_e32 v9, v2, v7
	ds_read2_b32 v[6:7], v13 offset0:28 offset1:30
	ds_write2_b32 v13, v8, v9 offset0:20 offset1:22
	s_waitcnt lgkmcnt(2)
	v_mul_f32_e32 v4, v2, v4
	v_mul_f32_e32 v5, v2, v5
	ds_write2_b32 v13, v4, v5 offset0:24 offset1:26
	s_waitcnt lgkmcnt(2)
	v_mul_f32_e32 v4, v2, v6
	v_mul_f32_e32 v5, v2, v7
	ds_write2_b32 v13, v4, v5 offset0:28 offset1:30
	s_waitcnt lgkmcnt(0)
	s_barrier
	ds_read2_b32 v[4:5], v13 offset0:1 offset1:3
	ds_read_b32 v6, v3 offset:61440
	ds_read_b32 v10, v12 offset:18548
	s_waitcnt lgkmcnt(1)
	v_fma_f32 v4, v14, v6, v4
	ds_write_b32 v12, v4 offset:18436
	ds_read_b32 v8, v3 offset:63488
	v_add_u32_e32 v4, 0xf000, v3
	ds_read2_b32 v[6:7], v13 offset0:5 offset1:7
	s_waitcnt lgkmcnt(1)
	v_fmac_f32_e32 v5, v14, v8
	ds_write_b32 v12, v5 offset:18444
	ds_read_b32 v5, v4 offset:4096
	s_waitcnt lgkmcnt(0)
	v_fma_f32 v5, v14, v5, v6
	ds_write_b32 v12, v5 offset:18452
	ds_read_b32 v5, v4 offset:6144
	ds_read2_b32 v[8:9], v13 offset0:9 offset1:11
	s_waitcnt lgkmcnt(1)
	v_fmac_f32_e32 v7, v14, v5
	ds_write_b32 v12, v7 offset:18460
	ds_read_b32 v5, v4 offset:8192
	s_waitcnt lgkmcnt(0)
	v_fma_f32 v5, v14, v5, v8
	ds_write_b32 v12, v5 offset:18468
	ds_read_b32 v5, v4 offset:10240
	s_waitcnt lgkmcnt(0)
	v_fmac_f32_e32 v9, v14, v5
	ds_write_b32 v12, v9 offset:18476
	ds_read_b32 v5, v4 offset:12288
	ds_read2_b32 v[6:7], v13 offset0:13 offset1:15
	s_waitcnt lgkmcnt(0)
	v_fma_f32 v5, v14, v5, v6
	ds_write_b32 v12, v5 offset:18484
	ds_read_b32 v5, v4 offset:14336
	s_waitcnt lgkmcnt(0)
	v_fmac_f32_e32 v7, v14, v5
	ds_write_b32 v12, v7 offset:18492
	ds_read_b32 v5, v4 offset:16384
	ds_read2_b32 v[6:7], v13 offset0:17 offset1:19
	s_waitcnt lgkmcnt(0)
	v_fma_f32 v5, v2, v5, v6
	ds_write_b32 v12, v5 offset:18500
	ds_read_b32 v5, v4 offset:18432
	s_waitcnt lgkmcnt(0)
	v_fmac_f32_e32 v7, v2, v5
	ds_write_b32 v12, v7 offset:18508
	ds_read2_b32 v[6:7], v13 offset0:21 offset1:23
	ds_read_b32 v5, v4 offset:20480
	s_waitcnt lgkmcnt(0)
	v_fma_f32 v5, v2, v5, v6
	ds_write_b32 v12, v5 offset:18516
	ds_read_b32 v5, v4 offset:22528
	ds_read2_b32 v[8:9], v13 offset0:25 offset1:27
	s_waitcnt lgkmcnt(1)
	v_fmac_f32_e32 v7, v2, v5
	ds_write_b32 v12, v7 offset:18524
	ds_read_b32 v5, v4 offset:24576
	s_waitcnt lgkmcnt(0)
	v_fma_f32 v5, v2, v5, v8
	ds_write_b32 v12, v5 offset:18532
	ds_read_b32 v5, v4 offset:26624
	s_waitcnt lgkmcnt(0)
	v_fmac_f32_e32 v9, v2, v5
	ds_write_b32 v12, v9 offset:18540
	ds_read_b32 v5, v4 offset:28672
	s_waitcnt lgkmcnt(0)
	v_fmac_f32_e32 v10, v2, v5
	ds_write_b32 v12, v10 offset:18548
	s_and_saveexec_b64 s[4:5], vcc
	s_cbranch_execz .LBB0_567
	ds_read_b32 v4, v4 offset:30720
	ds_read_b32 v5, v0 offset:18556
	s_waitcnt lgkmcnt(0)
	v_fmac_f32_e32 v5, v2, v4
	ds_write_b32 v0, v5 offset:18556

; DI unsigned pack2(float a, float b) { fv2 v = {a, b}; return __builtin_bit_cast(unsigned, __builtin_convertvector(v, bfv2)); }
; DI float bflo(unsigned u) { return __uint_as_float(u << 16); }
; DI float bfhi(unsigned u) { return __uint_as_float(u & 0xffff0000u); }
; DI float bf2f(bf16_t u) { return __uint_as_float(((unsigned)u) << 16); }
; DI float sigmoidf_(float x) { return __builtin_amdgcn_rcpf(1.f + __expf(-x)); }
; DI float siluf_(float x) { return x * __builtin_amdgcn_rcpf(1.f + __expf(-x)); }
; DI float xor32_sum(float x) { auto r = __builtin_amdgcn_permlane32_swap(__float_as_uint(x), __float_as_uint(x), false, false); return __uint_as_float(r[0]) + __uint_as_float(r[1]); }
; DI void nsa_item(const Params& p, int l_, int item, char* smraw, bool wr = true) {
;     ...
;   const float g0 = sigmoidf_(bf2f(hb[mrow * HS + C_GATE + 0 * 8 + H]));
;   const float g1 = sigmoidf_(bf2f(hb[mrow * HS + C_GATE + 1 * 8 + H]));
;   const float g2 = sigmoidf_(bf2f(hb[mrow * HS + C_GATE + 2 * 8 + H]));
;     ...
;   lt = xor32_sum(l);
;   inv = (lt > 0.f) ? 1.f / lt : 0.f;
; #pragma unroll
;   for (int e = 0; e < 16; ++e) { ot[0][e] += g1 * inv * o[0][e]; ot[1][e] += g1 * inv * o[1][e]; }
; #pragma unroll
;   for (int dt = 0; dt < 2; ++dt)
; #pragma unroll
;     for (int q = 0; q < 4; ++q) {
;       const int d = 32 * dt + 8 * q + 4 * h;
;       bf16_t* zp = hw + mrow * HS + C_AZ + H * 64 + d;
;       const uint2 z = *(const uint2*)zp;
;       uint2 ov;
;       ov.x = pack2(ot[dt][4 * q] * siluf_(bflo(z.x)), ot[dt][4 * q + 1] * siluf_(bfhi(z.x)));
;       ov.y = pack2(ot[dt][4 * q + 2] * siluf_(bflo(z.y)), ot[dt][4 * q + 3] * siluf_(bfhi(z.y)));
;       if (wr) *(uint2*)zp = ov;
;     }
.LBB0_642:
	v_cmp_eq_u32_e32 vcc, 0, v201
	s_and_saveexec_b64 s[98:99], vcc
	s_cbranch_execz .Lpf_nsa
	v_readlane_b32 s100, v252, 56
	v_readlane_b32 s101, v252, 57
	v_mov_b32_e32 v244, 1
	v_mov_b32_e32 v245, 1
	s_nop 2
	global_atomic_add v243, v1, v244, s[100:101] sc0
.Lpf_nsa:
	s_or_b64 exec, exec, s[98:99]
	v_readlane_b32 s0, v252, 62
	v_readlane_b32 s1, v252, 63
	s_movk_i32 s2, 0x1e00
	v_lshlrev_b32_e32 v0, 1, v234
	v_mov_b64_e32 v[2:3], s[0:1]
	v_mad_u64_u32 v[2:3], s[0:1], v210, s2, v[2:3]
	v_mad_i32_i24 v3, v211, s2, v3
	v_lshl_add_u64 v[2:3], v[2:3], 0, v[0:1]
	v_lshlrev_b32_e32 v0, 3, v230
	v_lshl_add_u64 v[2:3], v[2:3], 0, v[0:1]
	s_mov_b32 s0, 0x32a4000
	v_add_co_u32_e32 v10, vcc, s0, v2
	s_mov_b64 s[0:1], 0x32a4f00
	s_nop 0
	v_addc_co_u32_e32 v11, vcc, 0, v3, vcc
	global_load_dwordx2 v[18:19], v[10:11], off offset:3840
	v_lshl_add_u64 v[2:3], v[2:3], 0, s[0:1]
	global_load_dwordx2 v[16:17], v[2:3], off offset:16
	v_lshlrev_b32_e32 v4, 16, v231
	v_lshlrev_b32_e32 v5, 16, v232
	v_mul_f32_e32 v4, 0xbfb8aa3b, v4
	v_mul_f32_e32 v5, 0xbfb8aa3b, v5
	v_exp_f32_e32 v4, v4
	v_exp_f32_e32 v5, v5
	v_mov_b32_e32 v212, v214
	v_lshlrev_b32_e32 v0, 16, v233
	v_add_f32_e32 v24, 1.0, v4
	v_add_f32_e32 v25, 1.0, v5
	global_load_dwordx2 v[14:15], v[2:3], off offset:32
	global_load_dwordx2 v[12:13], v[2:3], off offset:48
	global_load_dwordx2 v[8:9], v[2:3], off offset:80
	global_load_dwordx2 v[6:7], v[2:3], off offset:96
	global_load_dwordx2 v[4:5], v[2:3], off offset:112
	v_permlane32_swap_b32_e32 v214, v212
	v_mul_f32_e32 v0, 0xbfb8aa3b, v0
	v_pk_add_f32 v[20:21], v[214:215], v[212:213]
	v_exp_f32_e32 v0, v0
	v_div_scale_f32 v22, s[0:1], v21, v21, 1.0
	v_div_scale_f32 v26, s[0:1], v20, v20, 1.0
	v_rcp_f32_e32 v28, v22
	v_rcp_f32_e32 v29, v26
	v_add_f32_e32 v0, 1.0, v0
	v_rcp_f32_e32 v30, v0
	v_rcp_f32_e32 v0, v24
	v_fma_f32 v24, -v22, v28, 1.0
	v_div_scale_f32 v23, vcc, 1.0, v21, 1.0
	v_rcp_f32_e32 v31, v25
	v_fma_f32 v25, -v26, v29, 1.0
	v_fmac_f32_e32 v28, v24, v28
	v_div_scale_f32 v27, s[36:37], 1.0, v20, 1.0
	v_fmac_f32_e32 v29, v25, v29
	v_mul_f32_e32 v128, v23, v28
	v_mul_f32_e32 v129, v27, v29
	v_fma_f32 v24, -v22, v128, v23
	v_fma_f32 v25, -v26, v129, v27
	v_fmac_f32_e32 v128, v24, v28
	v_fmac_f32_e32 v129, v25, v29
	v_fma_f32 v22, -v22, v128, v23
	v_fma_f32 v23, -v26, v129, v27
	v_div_fmas_f32 v22, v22, v28, v128
	s_mov_b64 vcc, s[36:37]
	v_div_fixup_f32 v22, v22, v21, 1.0
	v_div_fmas_f32 v23, v23, v29, v129
	v_cmp_lt_f32_e32 vcc, 0, v21
	v_mul_f32_e32 v0, v0, v235
	v_div_fixup_f32 v23, v23, v20, 1.0
	v_cndmask_b32_e32 v21, 0, v22, vcc
	v_cmp_lt_f32_e32 vcc, 0, v20
	v_pk_mul_f32 v[24:25], v[64:65], v[0:1] op_sel_hi:[1,0]
	v_mul_f32_e32 v22, v30, v21
	v_cndmask_b32_e32 v20, 0, v23, vcc
	v_mul_f32_e32 v20, v31, v20
	v_pk_fma_f32 v[24:25], v[32:33], v[22:23], v[24:25] op_sel_hi:[1,0,1]
	s_movk_i32 s87, 0x1e00
	v_pk_fma_f32 v[24:25], v[96:97], v[20:21], v[24:25] op_sel_hi:[1,0,1]
	s_mov_b64 s[2:3], 0
	v_readlane_b32 s23, v251, 0
	s_waitcnt vmcnt(6)
	v_lshlrev_b32_e32 v26, 16, v18
	v_and_b32_e32 v27, 0xffff0000, v18
	v_lshlrev_b32_e32 v18, 16, v19
	v_mul_f32_e32 v21, 0xbfb8aa3b, v26
	v_mul_f32_e32 v23, 0xbfb8aa3b, v27
	v_mul_f32_e32 v28, 0xbfb8aa3b, v18
	v_exp_f32_e32 v21, v21
	v_exp_f32_e32 v23, v23
	v_and_b32_e32 v19, 0xffff0000, v19
	v_exp_f32_e32 v28, v28
	v_mul_f32_e32 v29, 0xbfb8aa3b, v19
	v_exp_f32_e32 v30, v29
	v_add_f32_e32 v21, 1.0, v21
	v_add_f32_e32 v23, 1.0, v23
	v_add_f32_e32 v31, 1.0, v28
	v_rcp_f32_e32 v28, v21
	v_rcp_f32_e32 v29, v23
	v_add_f32_e32 v21, 1.0, v30
	v_rcp_f32_e32 v30, v31
	v_rcp_f32_e32 v31, v21
	v_pk_mul_f32 v[26:27], v[28:29], v[26:27]
	v_pk_mul_f32 v[18:19], v[30:31], v[18:19]
	v_pk_mul_f32 v[24:25], v[24:25], v[26:27]
	v_pk_mul_f32 v[26:27], v[66:67], v[0:1] op_sel_hi:[1,0]
	v_cvt_pk_bf16_f32 v24, v24, v25
	v_pk_fma_f32 v[26:27], v[34:35], v[22:23], v[26:27] op_sel_hi:[1,0,1]
	s_nop 0
	v_pk_fma_f32 v[26:27], v[98:99], v[20:21], v[26:27] op_sel_hi:[1,0,1]
	s_nop 0
	v_pk_mul_f32 v[18:19], v[26:27], v[18:19]
	s_waitcnt vmcnt(5)
	v_lshlrev_b32_e32 v26, 16, v16
	v_cvt_pk_bf16_f32 v25, v18, v19
	global_load_dwordx2 v[18:19], v[2:3], off offset:64
	v_and_b32_e32 v27, 0xffff0000, v16
	v_mul_f32_e32 v16, 0xbfb8aa3b, v26
	v_mul_f32_e32 v21, 0xbfb8aa3b, v27
	v_exp_f32_e32 v16, v16
	v_exp_f32_e32 v21, v21
	global_store_dwordx2 v[10:11], v[24:25], off offset:3840
	v_pk_mul_f32 v[24:25], v[68:69], v[0:1] op_sel_hi:[1,0]
	v_add_f32_e32 v10, 1.0, v16
	v_add_f32_e32 v11, 1.0, v21
	v_rcp_f32_e32 v10, v10
	v_rcp_f32_e32 v11, v11
	v_pk_fma_f32 v[24:25], v[36:37], v[22:23], v[24:25] op_sel_hi:[1,0,1]
	v_lshlrev_b32_e32 v16, 16, v17
	v_pk_fma_f32 v[24:25], v[100:101], v[20:21], v[24:25] op_sel_hi:[1,0,1]
	v_and_b32_e32 v17, 0xffff0000, v17
	v_mul_f32_e32 v21, 0xbfb8aa3b, v16
	v_exp_f32_e32 v21, v21
	v_mul_f32_e32 v23, 0xbfb8aa3b, v17
	v_exp_f32_e32 v23, v23
	v_pk_mul_f32 v[10:11], v[10:11], v[26:27]
	v_pk_mul_f32 v[26:27], v[70:71], v[0:1] op_sel_hi:[1,0]
	v_pk_mul_f32 v[10:11], v[24:25], v[10:11]
	v_pk_fma_f32 v[26:27], v[38:39], v[22:23], v[26:27] op_sel_hi:[1,0,1]
	v_cvt_pk_bf16_f32 v10, v10, v11
	v_add_f32_e32 v11, 1.0, v21
	v_rcp_f32_e32 v24, v11
	v_add_f32_e32 v11, 1.0, v23
	v_rcp_f32_e32 v25, v11
	v_pk_fma_f32 v[26:27], v[102:103], v[20:21], v[26:27] op_sel_hi:[1,0,1]
	v_pk_mul_f32 v[16:17], v[24:25], v[16:17]
	s_nop 0
	v_pk_mul_f32 v[16:17], v[26:27], v[16:17]
	v_pk_mul_f32 v[24:25], v[72:73], v[0:1] op_sel_hi:[1,0]
	v_cvt_pk_bf16_f32 v11, v16, v17
	s_waitcnt vmcnt(6)
; DI unsigned pack2(float a, float b) { fv2 v = {a, b}; return __builtin_bit_cast(unsigned, __builtin_convertvector(v, bfv2)); }
; DI float bflo(unsigned u) { return __uint_as_float(u << 16); }
; DI float bfhi(unsigned u) { return __uint_as_float(u & 0xffff0000u); }
; DI float siluf_(float x) { return x * __builtin_amdgcn_rcpf(1.f + __expf(-x)); }
; DI void nsa_item(const Params& p, int l_, int item, char* smraw, bool wr = true) {
;     ...
; #pragma unroll
;   for (int dt = 0; dt < 2; ++dt)
; #pragma unroll
;     for (int q = 0; q < 4; ++q) {
;       const int d = 32 * dt + 8 * q + 4 * h;
;       bf16_t* zp = hw + mrow * HS + C_AZ + H * 64 + d;
;       const uint2 z = *(const uint2*)zp;
;       uint2 ov;
;       ov.x = pack2(ot[dt][4 * q] * siluf_(bflo(z.x)), ot[dt][4 * q + 1] * siluf_(bfhi(z.x)));
;       ov.y = pack2(ot[dt][4 * q + 2] * siluf_(bflo(z.y)), ot[dt][4 * q + 3] * siluf_(bfhi(z.y)));
;       if (wr) *(uint2*)zp = ov;
;     }
	v_lshlrev_b32_e32 v16, 16, v14
	v_and_b32_e32 v17, 0xffff0000, v14
	v_mul_f32_e32 v14, 0xbfb8aa3b, v16
	v_mul_f32_e32 v21, 0xbfb8aa3b, v17
	v_exp_f32_e32 v14, v14
	v_exp_f32_e32 v21, v21
	global_store_dwordx2 v[2:3], v[10:11], off offset:16
	v_pk_fma_f32 v[24:25], v[40:41], v[22:23], v[24:25] op_sel_hi:[1,0,1]
	v_add_f32_e32 v10, 1.0, v14
	v_add_f32_e32 v11, 1.0, v21
	v_rcp_f32_e32 v10, v10
	v_rcp_f32_e32 v11, v11
	v_lshlrev_b32_e32 v14, 16, v15
	v_and_b32_e32 v15, 0xffff0000, v15
	v_pk_fma_f32 v[24:25], v[104:105], v[20:21], v[24:25] op_sel_hi:[1,0,1]
	v_pk_mul_f32 v[10:11], v[10:11], v[16:17]
	v_mul_f32_e32 v16, 0xbfb8aa3b, v14
	v_exp_f32_e32 v16, v16
	v_mul_f32_e32 v17, 0xbfb8aa3b, v15
	v_exp_f32_e32 v17, v17
	v_pk_mul_f32 v[10:11], v[24:25], v[10:11]
	v_pk_mul_f32 v[24:25], v[74:75], v[0:1] op_sel_hi:[1,0]
	v_cvt_pk_bf16_f32 v10, v10, v11
	v_add_f32_e32 v11, 1.0, v16
	v_rcp_f32_e32 v16, v11
	v_add_f32_e32 v11, 1.0, v17
	v_rcp_f32_e32 v17, v11
	v_pk_fma_f32 v[24:25], v[42:43], v[22:23], v[24:25] op_sel_hi:[1,0,1]
	v_pk_mul_f32 v[14:15], v[16:17], v[14:15]
	v_pk_fma_f32 v[24:25], v[106:107], v[20:21], v[24:25] op_sel_hi:[1,0,1]
	s_nop 0
	v_pk_mul_f32 v[14:15], v[24:25], v[14:15]
	s_nop 0
	v_cvt_pk_bf16_f32 v11, v14, v15
	s_waitcnt vmcnt(6)
	v_lshlrev_b32_e32 v14, 16, v12
	v_and_b32_e32 v15, 0xffff0000, v12
	v_mul_f32_e32 v12, 0xbfb8aa3b, v14
	v_mul_f32_e32 v16, 0xbfb8aa3b, v15
	v_exp_f32_e32 v12, v12
	v_exp_f32_e32 v16, v16
	global_store_dwordx2 v[2:3], v[10:11], off offset:32
	v_add_f32_e32 v10, 1.0, v12
	v_add_f32_e32 v11, 1.0, v16
	v_rcp_f32_e32 v10, v10
	v_rcp_f32_e32 v11, v11
	v_lshlrev_b32_e32 v12, 16, v13
	v_and_b32_e32 v13, 0xffff0000, v13
	v_pk_mul_f32 v[16:17], v[76:77], v[0:1] op_sel_hi:[1,0]
	v_pk_mul_f32 v[10:11], v[10:11], v[14:15]
	v_mul_f32_e32 v14, 0xbfb8aa3b, v12
	v_exp_f32_e32 v14, v14
	v_mul_f32_e32 v15, 0xbfb8aa3b, v13
	v_pk_fma_f32 v[16:17], v[44:45], v[22:23], v[16:17] op_sel_hi:[1,0,1]
	v_exp_f32_e32 v15, v15
	v_pk_fma_f32 v[16:17], v[108:109], v[20:21], v[16:17] op_sel_hi:[1,0,1]
	s_nop 0
	v_pk_mul_f32 v[10:11], v[16:17], v[10:11]
	v_pk_mul_f32 v[16:17], v[78:79], v[0:1] op_sel_hi:[1,0]
	v_cvt_pk_bf16_f32 v10, v10, v11
	v_add_f32_e32 v11, 1.0, v14
	v_rcp_f32_e32 v14, v11
	v_add_f32_e32 v11, 1.0, v15
	v_rcp_f32_e32 v15, v11
	v_pk_fma_f32 v[16:17], v[46:47], v[22:23], v[16:17] op_sel_hi:[1,0,1]
	v_pk_mul_f32 v[12:13], v[14:15], v[12:13]
	v_pk_fma_f32 v[16:17], v[110:111], v[20:21], v[16:17] op_sel_hi:[1,0,1]
	s_nop 0
	v_pk_mul_f32 v[12:13], v[16:17], v[12:13]
	v_pk_mul_f32 v[16:17], v[82:83], v[0:1] op_sel_hi:[1,0]
	v_cvt_pk_bf16_f32 v11, v12, v13
	s_waitcnt vmcnt(3)
; DI unsigned pack2(float a, float b) { fv2 v = {a, b}; return __builtin_bit_cast(unsigned, __builtin_convertvector(v, bfv2)); }
; DI float bflo(unsigned u) { return __uint_as_float(u << 16); }
; DI float bfhi(unsigned u) { return __uint_as_float(u & 0xffff0000u); }
; DI float siluf_(float x) { return x * __builtin_amdgcn_rcpf(1.f + __expf(-x)); }
; DI void nsa_item(const Params& p, int l_, int item, char* smraw, bool wr = true) {
;     ...
; #pragma unroll
;   for (int dt = 0; dt < 2; ++dt)
; #pragma unroll
;     for (int q = 0; q < 4; ++q) {
;       const int d = 32 * dt + 8 * q + 4 * h;
;       bf16_t* zp = hw + mrow * HS + C_AZ + H * 64 + d;
;       const uint2 z = *(const uint2*)zp;
;       uint2 ov;
;       ov.x = pack2(ot[dt][4 * q] * siluf_(bflo(z.x)), ot[dt][4 * q + 1] * siluf_(bfhi(z.x)));
;       ov.y = pack2(ot[dt][4 * q + 2] * siluf_(bflo(z.y)), ot[dt][4 * q + 3] * siluf_(bfhi(z.y)));
;       if (wr) *(uint2*)zp = ov;
;     }
;   __syncthreads();
	v_lshlrev_b32_e32 v12, 16, v18
	v_and_b32_e32 v13, 0xffff0000, v18
	v_mul_f32_e32 v14, 0xbfb8aa3b, v12
	v_mul_f32_e32 v15, 0xbfb8aa3b, v13
	v_exp_f32_e32 v14, v14
	v_exp_f32_e32 v15, v15
	global_store_dwordx2 v[2:3], v[10:11], off offset:48
	v_pk_fma_f32 v[16:17], v[50:51], v[22:23], v[16:17] op_sel_hi:[1,0,1]
	v_add_f32_e32 v10, 1.0, v14
	v_add_f32_e32 v11, 1.0, v15
	v_rcp_f32_e32 v10, v10
	v_rcp_f32_e32 v11, v11
	v_pk_mul_f32 v[14:15], v[80:81], v[0:1] op_sel_hi:[1,0]
	v_pk_fma_f32 v[16:17], v[114:115], v[20:21], v[16:17] op_sel_hi:[1,0,1]
	v_pk_fma_f32 v[14:15], v[48:49], v[22:23], v[14:15] op_sel_hi:[1,0,1]
	v_pk_mul_f32 v[10:11], v[10:11], v[12:13]
	v_pk_fma_f32 v[14:15], v[112:113], v[20:21], v[14:15] op_sel_hi:[1,0,1]
	v_lshlrev_b32_e32 v12, 16, v19
	v_pk_mul_f32 v[10:11], v[14:15], v[10:11]
	v_and_b32_e32 v13, 0xffff0000, v19
	v_mul_f32_e32 v14, 0xbfb8aa3b, v12
	v_exp_f32_e32 v14, v14
	v_mul_f32_e32 v15, 0xbfb8aa3b, v13
	v_exp_f32_e32 v15, v15
	v_cvt_pk_bf16_f32 v10, v10, v11
	v_add_f32_e32 v11, 1.0, v14
	v_rcp_f32_e32 v14, v11
	v_add_f32_e32 v11, 1.0, v15
	v_rcp_f32_e32 v15, v11
	s_nop 0
	v_pk_mul_f32 v[12:13], v[14:15], v[12:13]
	s_nop 0
	v_pk_mul_f32 v[12:13], v[16:17], v[12:13]
	s_nop 0
	v_cvt_pk_bf16_f32 v11, v12, v13
	v_lshlrev_b32_e32 v12, 16, v8
	v_and_b32_e32 v13, 0xffff0000, v8
	v_mul_f32_e32 v8, 0xbfb8aa3b, v12
	v_exp_f32_e32 v8, v8
	v_mul_f32_e32 v14, 0xbfb8aa3b, v13
	v_exp_f32_e32 v14, v14
	global_store_dwordx2 v[2:3], v[10:11], off offset:64
	v_add_f32_e32 v8, 1.0, v8
	v_rcp_f32_e32 v10, v8
	v_add_f32_e32 v8, 1.0, v14
	v_rcp_f32_e32 v11, v8
	v_lshlrev_b32_e32 v8, 16, v9
	v_and_b32_e32 v9, 0xffff0000, v9
	v_pk_mul_f32 v[14:15], v[84:85], v[0:1] op_sel_hi:[1,0]
	v_pk_mul_f32 v[10:11], v[10:11], v[12:13]
	v_mul_f32_e32 v12, 0xbfb8aa3b, v8
	v_exp_f32_e32 v12, v12
	v_mul_f32_e32 v13, 0xbfb8aa3b, v9
	v_pk_fma_f32 v[14:15], v[52:53], v[22:23], v[14:15] op_sel_hi:[1,0,1]
	v_exp_f32_e32 v13, v13
	v_pk_fma_f32 v[14:15], v[116:117], v[20:21], v[14:15] op_sel_hi:[1,0,1]
	s_nop 0
	v_pk_mul_f32 v[10:11], v[14:15], v[10:11]
	v_pk_mul_f32 v[14:15], v[86:87], v[0:1] op_sel_hi:[1,0]
	v_cvt_pk_bf16_f32 v10, v10, v11
	v_add_f32_e32 v11, 1.0, v12
	v_rcp_f32_e32 v12, v11
	v_add_f32_e32 v11, 1.0, v13
	v_rcp_f32_e32 v13, v11
	v_pk_fma_f32 v[14:15], v[54:55], v[22:23], v[14:15] op_sel_hi:[1,0,1]
	v_pk_mul_f32 v[8:9], v[12:13], v[8:9]
	v_pk_fma_f32 v[14:15], v[118:119], v[20:21], v[14:15] op_sel_hi:[1,0,1]
	s_nop 0
	v_pk_mul_f32 v[8:9], v[14:15], v[8:9]
	s_nop 0
	v_cvt_pk_bf16_f32 v11, v8, v9
	v_lshlrev_b32_e32 v8, 16, v6
	v_and_b32_e32 v9, 0xffff0000, v6
	v_mul_f32_e32 v6, 0xbfb8aa3b, v8
	v_exp_f32_e32 v6, v6
	v_mul_f32_e32 v12, 0xbfb8aa3b, v9
	v_exp_f32_e32 v12, v12
	global_store_dwordx2 v[2:3], v[10:11], off offset:80
	v_add_f32_e32 v6, 1.0, v6
	v_rcp_f32_e32 v10, v6
	v_add_f32_e32 v6, 1.0, v12
	v_rcp_f32_e32 v11, v6
	v_lshlrev_b32_e32 v6, 16, v7
	v_and_b32_e32 v7, 0xffff0000, v7
	v_pk_mul_f32 v[12:13], v[88:89], v[0:1] op_sel_hi:[1,0]
	v_pk_mul_f32 v[8:9], v[10:11], v[8:9]
	v_mul_f32_e32 v10, 0xbfb8aa3b, v6
	v_exp_f32_e32 v10, v10
	v_mul_f32_e32 v11, 0xbfb8aa3b, v7
	v_pk_fma_f32 v[12:13], v[56:57], v[22:23], v[12:13] op_sel_hi:[1,0,1]
	v_exp_f32_e32 v11, v11
	v_pk_fma_f32 v[12:13], v[120:121], v[20:21], v[12:13] op_sel_hi:[1,0,1]
	s_nop 0
	v_pk_mul_f32 v[8:9], v[12:13], v[8:9]
	v_pk_mul_f32 v[12:13], v[90:91], v[0:1] op_sel_hi:[1,0]
	v_cvt_pk_bf16_f32 v8, v8, v9
	v_add_f32_e32 v9, 1.0, v10
	v_rcp_f32_e32 v10, v9
	v_add_f32_e32 v9, 1.0, v11
	v_rcp_f32_e32 v11, v9
	v_pk_fma_f32 v[12:13], v[58:59], v[22:23], v[12:13] op_sel_hi:[1,0,1]
	v_pk_mul_f32 v[6:7], v[10:11], v[6:7]
	v_pk_fma_f32 v[12:13], v[122:123], v[20:21], v[12:13] op_sel_hi:[1,0,1]
	s_nop 0
	v_pk_mul_f32 v[6:7], v[12:13], v[6:7]
	s_nop 0
	v_cvt_pk_bf16_f32 v9, v6, v7
	v_lshlrev_b32_e32 v6, 16, v4
	v_and_b32_e32 v7, 0xffff0000, v4
	v_mul_f32_e32 v4, 0xbfb8aa3b, v6
	v_exp_f32_e32 v4, v4
	v_mul_f32_e32 v10, 0xbfb8aa3b, v7
	v_exp_f32_e32 v10, v10
	global_store_dwordx2 v[2:3], v[8:9], off offset:96
	v_add_f32_e32 v4, 1.0, v4
	v_rcp_f32_e32 v8, v4
	v_add_f32_e32 v4, 1.0, v10
	v_rcp_f32_e32 v9, v4
	v_lshlrev_b32_e32 v4, 16, v5
	v_and_b32_e32 v5, 0xffff0000, v5
	v_pk_mul_f32 v[10:11], v[92:93], v[0:1] op_sel_hi:[1,0]
	v_pk_mul_f32 v[6:7], v[8:9], v[6:7]
	v_mul_f32_e32 v8, 0xbfb8aa3b, v4
	v_exp_f32_e32 v8, v8
	v_mul_f32_e32 v9, 0xbfb8aa3b, v5
	v_pk_fma_f32 v[10:11], v[60:61], v[22:23], v[10:11] op_sel_hi:[1,0,1]
	v_exp_f32_e32 v9, v9
	v_pk_fma_f32 v[10:11], v[124:125], v[20:21], v[10:11] op_sel_hi:[1,0,1]
	s_nop 0
	v_pk_mul_f32 v[6:7], v[10:11], v[6:7]
	v_pk_mul_f32 v[10:11], v[94:95], v[0:1] op_sel_hi:[1,0]
	v_cvt_pk_bf16_f32 v6, v6, v7
	v_add_f32_e32 v7, 1.0, v8
	v_rcp_f32_e32 v8, v7
	v_add_f32_e32 v7, 1.0, v9
	v_rcp_f32_e32 v9, v7
	v_pk_fma_f32 v[10:11], v[62:63], v[22:23], v[10:11] op_sel_hi:[1,0,1]
	v_pk_mul_f32 v[4:5], v[8:9], v[4:5]
	v_pk_fma_f32 v[10:11], v[126:127], v[20:21], v[10:11] op_sel_hi:[1,0,1]
	s_nop 0
	v_pk_mul_f32 v[4:5], v[10:11], v[4:5]
	s_nop 0
	v_cvt_pk_bf16_f32 v7, v4, v5
	global_store_dwordx2 v[2:3], v[6:7], off offset:112
	s_waitcnt lgkmcnt(0)
	s_barrier

; DI unsigned pack2(float a, float b) { fv2 v = {a, b}; return __builtin_bit_cast(unsigned, __builtin_convertvector(v, bfv2)); }
; DI float bflo(unsigned u) { return __uint_as_float(u << 16); }
; DI float bfhi(unsigned u) { return __uint_as_float(u & 0xffff0000u); }
; DI float siluf_(float x) { return x * __builtin_amdgcn_rcpf(1.f + __expf(-x)); }
; DI float xor32_sum(float x) { auto r = __builtin_amdgcn_permlane32_swap(__float_as_uint(x), __float_as_uint(x), false, false); return __uint_as_float(r[0]) + __uint_as_float(r[1]); }
; DI void swa_item(const Params& p, int l_, int item, char* smraw, bool wr = true) {
;     ...
;   const float lt = xor32_sum(l);
;   const float inv = (lt > 0.f) ? 1.f / lt : 0.f;
; #pragma unroll
;   for (int dt = 0; dt < 2; ++dt)
; #pragma unroll
;     for (int q = 0; q < 4; ++q) {
;       const int d = 32 * dt + 8 * q + 4 * h;
;       bf16_t* zp = hw + mrow * HS + C_BZ + H * 64 + d;
;       const uint2 z = *(const uint2*)zp;
;       uint2 ov;
;       ov.x = pack2(inv * o[dt][4 * q] * siluf_(bflo(z.x)), inv * o[dt][4 * q + 1] * siluf_(bfhi(z.x)));
;       ov.y = pack2(inv * o[dt][4 * q + 2] * siluf_(bflo(z.y)), inv * o[dt][4 * q + 3] * siluf_(bfhi(z.y)));
;       if (wr) *(uint2*)zp = ov;
;     }
.Lpf_swa:
	s_or_b64 exec, exec, s[98:99]
	v_mov_b32_e32 v34, v125
	s_nop 1
	v_permlane32_swap_b32_e32 v125, v34
	v_add_f32_e32 v34, v125, v34
	v_div_scale_f32 v35, s[2:3], v34, v34, 1.0
	v_rcp_f32_e32 v38, v35
	s_movk_i32 s0, 0x1e00
	v_mad_u64_u32 v[36:37], s[2:3], v122, s0, 0
	v_fma_f32 v39, -v35, v38, 1.0
	v_fmac_f32_e32 v38, v39, v38
	v_div_scale_f32 v39, vcc, 1.0, v34, 1.0
	v_mul_f32_e32 v40, v39, v38
	v_mad_i32_i24 v37, v123, s0, v37
	v_lshlrev_b32_e32 v0, 6, v131
	v_fma_f32 v41, -v35, v40, v39
	v_fmac_f32_e32 v40, v41, v38
	v_lshl_add_u64 v[36:37], s[12:13], 0, v[36:37]
	v_lshlrev_b32_e32 v0, 1, v0
	v_fma_f32 v35, -v35, v40, v39
	v_lshl_add_u64 v[36:37], v[36:37], 0, v[0:1]
	v_lshlrev_b32_e32 v0, 3, v130
	v_div_fmas_f32 v35, v35, v38, v40
	v_lshl_add_u64 v[38:39], v[36:37], 0, v[0:1]
	s_mov_b64 s[2:3], 0x32a5700
	s_mov_b32 s0, 0x32a5000
	v_lshl_add_u64 v[36:37], v[38:39], 0, s[2:3]
	v_add_co_u32_e32 v38, vcc, s0, v38
	v_cmp_lt_f32_e64 s[36:37], 0, v34
	s_nop 0
	v_addc_co_u32_e32 v39, vcc, 0, v39, vcc
	global_load_dwordx2 v[40:41], v[38:39], off offset:1792
	v_div_fixup_f32 v34, v35, v34, 1.0
	v_cndmask_b32_e64 v34, 0, v34, s[36:37]
	v_pk_mul_f32 v[2:3], v[2:3], v[34:35] op_sel_hi:[1,0]
	v_pk_mul_f32 v[4:5], v[4:5], v[34:35] op_sel_hi:[1,0]
	v_pk_mul_f32 v[6:7], v[6:7], v[34:35] op_sel_hi:[1,0]
	v_pk_mul_f32 v[8:9], v[8:9], v[34:35] op_sel_hi:[1,0]
	s_movk_i32 s87, 0x1e00
	s_mov_b32 s20, s38
	s_waitcnt vmcnt(0)
	v_lshlrev_b32_e32 v42, 16, v40
	v_mul_f32_e32 v0, 0xbfb8aa3b, v42
	v_exp_f32_e32 v0, v0
	v_and_b32_e32 v43, 0xffff0000, v40
	v_lshlrev_b32_e32 v40, 16, v41
	v_and_b32_e32 v41, 0xffff0000, v41
	v_add_f32_e32 v0, 1.0, v0
	v_rcp_f32_e32 v44, v0
	v_mul_f32_e32 v0, 0xbfb8aa3b, v43
	v_exp_f32_e32 v0, v0
	s_nop 0
	v_add_f32_e32 v0, 1.0, v0
	v_rcp_f32_e32 v45, v0
	v_mul_f32_e32 v0, 0xbfb8aa3b, v40
	v_exp_f32_e32 v0, v0
	v_pk_mul_f32 v[42:43], v[44:45], v[42:43]
	s_nop 0
	v_pk_mul_f32 v[2:3], v[2:3], v[42:43]
	v_add_f32_e32 v0, 1.0, v0
	v_rcp_f32_e32 v42, v0
	v_mul_f32_e32 v0, 0xbfb8aa3b, v41
	v_exp_f32_e32 v0, v0
	v_cvt_pk_bf16_f32 v2, v2, v3
	v_add_f32_e32 v0, 1.0, v0
	v_rcp_f32_e32 v43, v0
	s_nop 0
	v_pk_mul_f32 v[40:41], v[42:43], v[40:41]
	s_nop 0
	v_pk_mul_f32 v[4:5], v[4:5], v[40:41]
	s_nop 0
	v_cvt_pk_bf16_f32 v3, v4, v5
	global_store_dwordx2 v[38:39], v[2:3], off offset:1792
	global_load_dwordx2 v[2:3], v[36:37], off offset:16
	s_waitcnt vmcnt(0)
	v_lshlrev_b32_e32 v4, 16, v2
	v_mul_f32_e32 v0, 0xbfb8aa3b, v4
	v_exp_f32_e32 v0, v0
	v_and_b32_e32 v5, 0xffff0000, v2
	v_add_f32_e32 v0, 1.0, v0
	v_rcp_f32_e32 v38, v0
	v_mul_f32_e32 v0, 0xbfb8aa3b, v5
	v_exp_f32_e32 v0, v0
	s_nop 0
	v_add_f32_e32 v0, 1.0, v0
	v_rcp_f32_e32 v39, v0
	s_nop 0
	v_pk_mul_f32 v[4:5], v[38:39], v[4:5]
	s_nop 0
	v_pk_mul_f32 v[4:5], v[6:7], v[4:5]
	s_nop 0
	v_cvt_pk_bf16_f32 v2, v4, v5
	v_lshlrev_b32_e32 v4, 16, v3
	v_mul_f32_e32 v0, 0xbfb8aa3b, v4
	v_exp_f32_e32 v0, v0
	v_and_b32_e32 v5, 0xffff0000, v3
	v_add_f32_e32 v0, 1.0, v0
	v_rcp_f32_e32 v6, v0
	v_mul_f32_e32 v0, 0xbfb8aa3b, v5
	v_exp_f32_e32 v0, v0
	s_nop 0
	v_add_f32_e32 v0, 1.0, v0
	v_rcp_f32_e32 v7, v0
	s_nop 0
	v_pk_mul_f32 v[4:5], v[6:7], v[4:5]
	s_nop 0
	v_pk_mul_f32 v[4:5], v[8:9], v[4:5]
	v_pk_mul_f32 v[8:9], v[10:11], v[34:35] op_sel_hi:[1,0]
	v_cvt_pk_bf16_f32 v3, v4, v5
	global_store_dwordx2 v[36:37], v[2:3], off offset:16
	global_load_dwordx2 v[2:3], v[36:37], off offset:32
	s_waitcnt vmcnt(0)
	v_lshlrev_b32_e32 v4, 16, v2
	v_mul_f32_e32 v0, 0xbfb8aa3b, v4
	v_exp_f32_e32 v0, v0
	v_and_b32_e32 v5, 0xffff0000, v2
	v_add_f32_e32 v0, 1.0, v0
	v_rcp_f32_e32 v6, v0
	v_mul_f32_e32 v0, 0xbfb8aa3b, v5
	v_exp_f32_e32 v0, v0
	s_nop 0
	v_add_f32_e32 v0, 1.0, v0
	v_rcp_f32_e32 v7, v0
	s_nop 0
	v_pk_mul_f32 v[4:5], v[6:7], v[4:5]
	s_nop 0
	v_pk_mul_f32 v[4:5], v[8:9], v[4:5]
	v_pk_mul_f32 v[8:9], v[12:13], v[34:35] op_sel_hi:[1,0]
	v_cvt_pk_bf16_f32 v2, v4, v5
	v_lshlrev_b32_e32 v4, 16, v3
	v_mul_f32_e32 v0, 0xbfb8aa3b, v4
	v_exp_f32_e32 v0, v0
	v_and_b32_e32 v5, 0xffff0000, v3
	v_add_f32_e32 v0, 1.0, v0
	v_rcp_f32_e32 v6, v0
	v_mul_f32_e32 v0, 0xbfb8aa3b, v5
	v_exp_f32_e32 v0, v0
	s_nop 0
	v_add_f32_e32 v0, 1.0, v0
	v_rcp_f32_e32 v7, v0
	s_nop 0
	v_pk_mul_f32 v[4:5], v[6:7], v[4:5]
	s_nop 0
	v_pk_mul_f32 v[4:5], v[8:9], v[4:5]
	v_pk_mul_f32 v[8:9], v[14:15], v[34:35] op_sel_hi:[1,0]
	v_cvt_pk_bf16_f32 v3, v4, v5
	global_store_dwordx2 v[36:37], v[2:3], off offset:32
	global_load_dwordx2 v[2:3], v[36:37], off offset:48
	s_waitcnt vmcnt(0)
; DI unsigned pack2(float a, float b) { fv2 v = {a, b}; return __builtin_bit_cast(unsigned, __builtin_convertvector(v, bfv2)); }
; DI float bflo(unsigned u) { return __uint_as_float(u << 16); }
; DI float bfhi(unsigned u) { return __uint_as_float(u & 0xffff0000u); }
; DI float siluf_(float x) { return x * __builtin_amdgcn_rcpf(1.f + __expf(-x)); }
; DI void swa_item(const Params& p, int l_, int item, char* smraw, bool wr = true) {
;     ...
;   for (int dt = 0; dt < 2; ++dt)
; #pragma unroll
;     for (int q = 0; q < 4; ++q) {
;       const int d = 32 * dt + 8 * q + 4 * h;
;       bf16_t* zp = hw + mrow * HS + C_BZ + H * 64 + d;
;       const uint2 z = *(const uint2*)zp;
;       uint2 ov;
;       ov.x = pack2(inv * o[dt][4 * q] * siluf_(bflo(z.x)), inv * o[dt][4 * q + 1] * siluf_(bfhi(z.x)));
;       ov.y = pack2(inv * o[dt][4 * q + 2] * siluf_(bflo(z.y)), inv * o[dt][4 * q + 3] * siluf_(bfhi(z.y)));
;       if (wr) *(uint2*)zp = ov;
;     }
;   __syncthreads();
	v_lshlrev_b32_e32 v4, 16, v2
	v_mul_f32_e32 v0, 0xbfb8aa3b, v4
	v_exp_f32_e32 v0, v0
	v_and_b32_e32 v5, 0xffff0000, v2
	v_add_f32_e32 v0, 1.0, v0
	v_rcp_f32_e32 v6, v0
	v_mul_f32_e32 v0, 0xbfb8aa3b, v5
	v_exp_f32_e32 v0, v0
	s_nop 0
	v_add_f32_e32 v0, 1.0, v0
	v_rcp_f32_e32 v7, v0
	s_nop 0
	v_pk_mul_f32 v[4:5], v[6:7], v[4:5]
	s_nop 0
	v_pk_mul_f32 v[4:5], v[8:9], v[4:5]
	v_pk_mul_f32 v[8:9], v[16:17], v[34:35] op_sel_hi:[1,0]
	v_cvt_pk_bf16_f32 v2, v4, v5
	v_lshlrev_b32_e32 v4, 16, v3
	v_mul_f32_e32 v0, 0xbfb8aa3b, v4
	v_exp_f32_e32 v0, v0
	v_and_b32_e32 v5, 0xffff0000, v3
	v_add_f32_e32 v0, 1.0, v0
	v_rcp_f32_e32 v6, v0
	v_mul_f32_e32 v0, 0xbfb8aa3b, v5
	v_exp_f32_e32 v0, v0
	s_nop 0
	v_add_f32_e32 v0, 1.0, v0
	v_rcp_f32_e32 v7, v0
	s_nop 0
	v_pk_mul_f32 v[4:5], v[6:7], v[4:5]
	s_nop 0
	v_pk_mul_f32 v[4:5], v[8:9], v[4:5]
	v_pk_mul_f32 v[8:9], v[18:19], v[34:35] op_sel_hi:[1,0]
	v_cvt_pk_bf16_f32 v3, v4, v5
	global_store_dwordx2 v[36:37], v[2:3], off offset:48
	global_load_dwordx2 v[2:3], v[36:37], off offset:64
	s_waitcnt vmcnt(0)
	v_lshlrev_b32_e32 v4, 16, v2
	v_mul_f32_e32 v0, 0xbfb8aa3b, v4
	v_exp_f32_e32 v0, v0
	v_and_b32_e32 v5, 0xffff0000, v2
	v_add_f32_e32 v0, 1.0, v0
	v_rcp_f32_e32 v6, v0
	v_mul_f32_e32 v0, 0xbfb8aa3b, v5
	v_exp_f32_e32 v0, v0
	s_nop 0
	v_add_f32_e32 v0, 1.0, v0
	v_rcp_f32_e32 v7, v0
	s_nop 0
	v_pk_mul_f32 v[4:5], v[6:7], v[4:5]
	s_nop 0
	v_pk_mul_f32 v[4:5], v[8:9], v[4:5]
	v_pk_mul_f32 v[8:9], v[20:21], v[34:35] op_sel_hi:[1,0]
	v_cvt_pk_bf16_f32 v2, v4, v5
	v_lshlrev_b32_e32 v4, 16, v3
	v_mul_f32_e32 v0, 0xbfb8aa3b, v4
	v_exp_f32_e32 v0, v0
	v_and_b32_e32 v5, 0xffff0000, v3
	v_add_f32_e32 v0, 1.0, v0
	v_rcp_f32_e32 v6, v0
	v_mul_f32_e32 v0, 0xbfb8aa3b, v5
	v_exp_f32_e32 v0, v0
	s_nop 0
	v_add_f32_e32 v0, 1.0, v0
	v_rcp_f32_e32 v7, v0
	s_nop 0
	v_pk_mul_f32 v[4:5], v[6:7], v[4:5]
	s_nop 0
	v_pk_mul_f32 v[4:5], v[8:9], v[4:5]
	v_pk_mul_f32 v[8:9], v[22:23], v[34:35] op_sel_hi:[1,0]
	v_cvt_pk_bf16_f32 v3, v4, v5
	global_store_dwordx2 v[36:37], v[2:3], off offset:64
	global_load_dwordx2 v[2:3], v[36:37], off offset:80
	s_waitcnt vmcnt(0)
	v_lshlrev_b32_e32 v4, 16, v2
	v_mul_f32_e32 v0, 0xbfb8aa3b, v4
	v_exp_f32_e32 v0, v0
	v_and_b32_e32 v5, 0xffff0000, v2
	v_add_f32_e32 v0, 1.0, v0
	v_rcp_f32_e32 v6, v0
	v_mul_f32_e32 v0, 0xbfb8aa3b, v5
	v_exp_f32_e32 v0, v0
	s_nop 0
	v_add_f32_e32 v0, 1.0, v0
	v_rcp_f32_e32 v7, v0
	s_nop 0
	v_pk_mul_f32 v[4:5], v[6:7], v[4:5]
	s_nop 0
	v_pk_mul_f32 v[4:5], v[8:9], v[4:5]
	v_pk_mul_f32 v[8:9], v[24:25], v[34:35] op_sel_hi:[1,0]
	v_cvt_pk_bf16_f32 v2, v4, v5
	v_lshlrev_b32_e32 v4, 16, v3
	v_mul_f32_e32 v0, 0xbfb8aa3b, v4
	v_exp_f32_e32 v0, v0
	v_and_b32_e32 v5, 0xffff0000, v3
	v_add_f32_e32 v0, 1.0, v0
	v_rcp_f32_e32 v6, v0
	v_mul_f32_e32 v0, 0xbfb8aa3b, v5
	v_exp_f32_e32 v0, v0
	s_nop 0
	v_add_f32_e32 v0, 1.0, v0
	v_rcp_f32_e32 v7, v0
	s_nop 0
	v_pk_mul_f32 v[4:5], v[6:7], v[4:5]
	s_nop 0
	v_pk_mul_f32 v[4:5], v[8:9], v[4:5]
	v_pk_mul_f32 v[8:9], v[26:27], v[34:35] op_sel_hi:[1,0]
	v_cvt_pk_bf16_f32 v3, v4, v5
	global_store_dwordx2 v[36:37], v[2:3], off offset:80
	global_load_dwordx2 v[2:3], v[36:37], off offset:96
	s_waitcnt vmcnt(0)
	v_lshlrev_b32_e32 v4, 16, v2
	v_mul_f32_e32 v0, 0xbfb8aa3b, v4
	v_exp_f32_e32 v0, v0
	v_and_b32_e32 v5, 0xffff0000, v2
	v_add_f32_e32 v0, 1.0, v0
	v_rcp_f32_e32 v6, v0
	v_mul_f32_e32 v0, 0xbfb8aa3b, v5
	v_exp_f32_e32 v0, v0
	s_nop 0
	v_add_f32_e32 v0, 1.0, v0
	v_rcp_f32_e32 v7, v0
	s_nop 0
	v_pk_mul_f32 v[4:5], v[6:7], v[4:5]
	s_nop 0
	v_pk_mul_f32 v[4:5], v[8:9], v[4:5]
	v_pk_mul_f32 v[8:9], v[28:29], v[34:35] op_sel_hi:[1,0]
	v_cvt_pk_bf16_f32 v2, v4, v5
	v_lshlrev_b32_e32 v4, 16, v3
	v_mul_f32_e32 v0, 0xbfb8aa3b, v4
	v_exp_f32_e32 v0, v0
	v_and_b32_e32 v5, 0xffff0000, v3
	v_add_f32_e32 v0, 1.0, v0
	v_rcp_f32_e32 v6, v0
	v_mul_f32_e32 v0, 0xbfb8aa3b, v5
	v_exp_f32_e32 v0, v0
	s_nop 0
	v_add_f32_e32 v0, 1.0, v0
	v_rcp_f32_e32 v7, v0
	s_nop 0
	v_pk_mul_f32 v[4:5], v[6:7], v[4:5]
	s_nop 0
	v_pk_mul_f32 v[4:5], v[8:9], v[4:5]
	v_pk_mul_f32 v[8:9], v[30:31], v[34:35] op_sel_hi:[1,0]
	v_cvt_pk_bf16_f32 v3, v4, v5
	global_store_dwordx2 v[36:37], v[2:3], off offset:96
	global_load_dwordx2 v[2:3], v[36:37], off offset:112
	s_waitcnt vmcnt(0)
	v_lshlrev_b32_e32 v4, 16, v2
	v_mul_f32_e32 v0, 0xbfb8aa3b, v4
	v_exp_f32_e32 v0, v0
	v_and_b32_e32 v5, 0xffff0000, v2
	v_add_f32_e32 v0, 1.0, v0
	v_rcp_f32_e32 v6, v0
	v_mul_f32_e32 v0, 0xbfb8aa3b, v5
	v_exp_f32_e32 v0, v0
	s_nop 0
	v_add_f32_e32 v0, 1.0, v0
	v_rcp_f32_e32 v7, v0
	s_nop 0
	v_pk_mul_f32 v[4:5], v[6:7], v[4:5]
	s_nop 0
	v_pk_mul_f32 v[4:5], v[8:9], v[4:5]
	v_pk_mul_f32 v[8:9], v[32:33], v[34:35] op_sel_hi:[1,0]
	v_cvt_pk_bf16_f32 v2, v4, v5
	v_lshlrev_b32_e32 v4, 16, v3
	v_mul_f32_e32 v0, 0xbfb8aa3b, v4
	v_exp_f32_e32 v0, v0
	v_and_b32_e32 v5, 0xffff0000, v3
	v_add_f32_e32 v0, 1.0, v0
	v_rcp_f32_e32 v6, v0
	v_mul_f32_e32 v0, 0xbfb8aa3b, v5
	v_exp_f32_e32 v0, v0
	s_nop 0
	v_add_f32_e32 v0, 1.0, v0
	v_rcp_f32_e32 v7, v0
	s_nop 0
	v_pk_mul_f32 v[4:5], v[6:7], v[4:5]
	s_nop 0
	v_pk_mul_f32 v[4:5], v[8:9], v[4:5]
	s_nop 0
	v_cvt_pk_bf16_f32 v3, v4, v5
	global_store_dwordx2 v[36:37], v[2:3], off offset:112
	s_barrier
	s_cbranch_execnz .LBB0_512
	s_branch .LBB0_662

; DI bf16_t f2bf(float a) { return (bf16_t)(pack2(a, 0.f) & 0xffffu); }
; DI float bf2f(bf16_t u) { return __uint_as_float(((unsigned)u) << 16); }
; DI float siluf_(float x) { return x * __builtin_amdgcn_rcpf(1.f + __expf(-x)); }
; DI int bidx() { int b = blockIdx.x; asm volatile("" : "+s"(b)); return b; }
; DI float wave_sum_fast(float v) { v = fdpp_add(v, 0); v = fdpp_add(v, 1); v = fdpp_add(v, 2); v = fdpp_add(v, 3); v = xor16_sum(v); return xor32_sum(v); }
; DI void rwkv_post(const Params& p, int l) {
;     ...
;   for (int it = bidx(); it < NTOK / 16; it += gridDim.x) {
;     float y[8], v[8], z[8], bo[8];
; #pragma unroll
;     for (int q = 0; q < 8; ++q) {
;       const size_t m = (size_t)it * 16 + sub * 8 + q;
;       const int b = (int)(m >> 11), t = (int)(m & 2047);
;       y[q] = bf2f(yr[m * 256 + hd * 64 + lane]);
;       v[q] = bf2f(pr[((size_t)((b * 4 + hd) * 2048 + t)) * 384 + 3 * 64 + lane]);
;       z[q] = bf2f(hw[m * HS + C_CZ + hd * 64 + lane]);
;       bo[q] = bon[m * 4 + hd];
;     }
; #pragma unroll
;     for (int q = 0; q < 8; ++q) {
;       const size_t m = (size_t)it * 16 + sub * 8 + q;
;       const float mean = wave_sum_fast(y[q]) * (1.f / 64.f);
;       const float dlt = y[q] - mean;
;       const float var = wave_sum_fast(dlt * dlt) * (1.f / 64.f);
;       float o = dlt * rsqrtf(var + 64e-5f) * lw + lb + bo[q] * v[q];
;       o *= siluf_(z[q]);
;       hw[m * HS + C_CZ + hd * 64 + lane] = f2bf(o);
.LBB0_862:
	s_lshl_b32 s0, s2, 4
	v_mov_b32_e32 v99, 0
	v_add_u32_e32 v98, s0, v2
	s_movk_i32 s0, 0x7f8
	s_mov_b32 s41, 0
	v_lshrrev_b32_e32 v118, 9, v98
	v_lshlrev_b64 v[88:89], 9, v[98:99]
	v_and_or_b32 v118, v118, s21, v30
	v_lshl_add_u64 v[90:91], v[98:99], 4, v[8:9]
	v_lshl_add_u64 v[88:89], v[88:89], 0, v[4:5]
	v_lshlrev_b32_e32 v118, 11, v118
	v_mov_b64_e32 v[96:97], s[8:9]
	v_and_or_b32 v118, v98, s0, v118
	v_mad_u64_u32 v[96:97], s[0:1], v98, s12, v[96:97]
	v_mad_i64_i32 v[92:93], s[0:1], v118, s22, v[6:7]
	v_mov_b32_e32 v11, v1
	v_lshl_add_u64 v[96:97], v[96:97], 0, v[0:1]
	s_movk_i32 s40, 0x1200
	v_lshl_add_u64 v[96:97], v[96:97], 0, v[10:11]
	v_lshl_add_u64 v[94:95], v[92:93], 0, s[40:41]
	s_mov_b32 s40, 0x1b00
	v_lshl_add_u64 v[72:73], v[96:97], 0, s[40:41]
	s_mov_b32 s40, 0x3900
	v_lshl_add_u64 v[74:75], v[96:97], 0, s[40:41]
	s_mov_b32 s40, 0x5700
	v_lshl_add_u64 v[76:77], v[96:97], 0, s[40:41]
	s_mov_b32 s40, 0x7500
	v_lshl_add_u64 v[78:79], v[96:97], 0, s[40:41]
	s_mov_b32 s40, 0x9300
	v_lshl_add_u64 v[80:81], v[96:97], 0, s[40:41]
	s_mov_b32 s40, 0xb100
	v_lshl_add_u64 v[82:83], v[96:97], 0, s[40:41]
	s_mov_b32 s40, 0xcf00
	v_lshl_add_u64 v[84:85], v[96:97], 0, s[40:41]
	s_mov_b32 s40, 0xed00
	v_lshl_add_u64 v[86:87], v[96:97], 0, s[40:41]
	global_load_ushort v40, v[88:89], off
	global_load_ushort v41, v[88:89], off offset:512
	global_load_ushort v42, v[88:89], off offset:1024
	global_load_ushort v43, v[88:89], off offset:1536
	global_load_ushort v44, v[88:89], off offset:2048
	global_load_ushort v45, v[88:89], off offset:2560
	global_load_ushort v46, v[88:89], off offset:3072
	global_load_ushort v47, v[88:89], off offset:3584
	global_load_ushort v48, v[92:93], off
	global_load_ushort v49, v[92:93], off offset:768
	global_load_ushort v50, v[92:93], off offset:1536
	global_load_ushort v51, v[92:93], off offset:2304
	global_load_ushort v52, v[92:93], off offset:3072
	global_load_ushort v53, v[92:93], off offset:3840
	global_load_ushort v54, v[94:95], off
	global_load_ushort v55, v[94:95], off offset:768
	global_load_ushort v56, v[72:73], off
	global_load_ushort v57, v[74:75], off
	global_load_ushort v58, v[76:77], off
	global_load_ushort v59, v[78:79], off
	global_load_ushort v60, v[80:81], off
	global_load_ushort v61, v[82:83], off
	global_load_ushort v62, v[84:85], off
	global_load_ushort v63, v[86:87], off
	global_load_dword v64, v[90:91], off
	global_load_dword v65, v[90:91], off offset:16
	global_load_dword v66, v[90:91], off offset:32
	global_load_dword v67, v[90:91], off offset:48
	global_load_dword v68, v[90:91], off offset:64
	global_load_dword v69, v[90:91], off offset:80
	global_load_dword v70, v[90:91], off offset:96
	global_load_dword v71, v[90:91], off offset:112
	v_mov_b32_e32 v116, 0x3a27c5ac
	s_waitcnt vmcnt(0)
	v_lshlrev_b32_e32 v40, 16, v40
	v_lshlrev_b32_e32 v41, 16, v41
	v_lshlrev_b32_e32 v42, 16, v42
	v_lshlrev_b32_e32 v43, 16, v43
	v_lshlrev_b32_e32 v44, 16, v44
	v_lshlrev_b32_e32 v45, 16, v45
	v_lshlrev_b32_e32 v46, 16, v46
	v_lshlrev_b32_e32 v47, 16, v47
	v_lshlrev_b32_e32 v48, 16, v48
	v_lshlrev_b32_e32 v49, 16, v49
	v_lshlrev_b32_e32 v50, 16, v50
	v_lshlrev_b32_e32 v51, 16, v51
	v_lshlrev_b32_e32 v52, 16, v52
	v_lshlrev_b32_e32 v53, 16, v53
	v_lshlrev_b32_e32 v54, 16, v54
	v_lshlrev_b32_e32 v55, 16, v55
	v_lshlrev_b32_e32 v56, 16, v56
	v_lshlrev_b32_e32 v57, 16, v57
	v_lshlrev_b32_e32 v58, 16, v58
	v_lshlrev_b32_e32 v59, 16, v59
	v_lshlrev_b32_e32 v60, 16, v60
	v_lshlrev_b32_e32 v61, 16, v61
	v_lshlrev_b32_e32 v62, 16, v62
	v_lshlrev_b32_e32 v63, 16, v63
	v_add_f32_dpp v100, v40, v40 quad_perm:[1,0,3,2] row_mask:0xf bank_mask:0xf bound_ctrl:1
	v_add_f32_dpp v101, v41, v41 quad_perm:[1,0,3,2] row_mask:0xf bank_mask:0xf bound_ctrl:1
	v_add_f32_dpp v102, v42, v42 quad_perm:[1,0,3,2] row_mask:0xf bank_mask:0xf bound_ctrl:1
	v_add_f32_dpp v103, v43, v43 quad_perm:[1,0,3,2] row_mask:0xf bank_mask:0xf bound_ctrl:1
	v_add_f32_dpp v104, v44, v44 quad_perm:[1,0,3,2] row_mask:0xf bank_mask:0xf bound_ctrl:1
	v_add_f32_dpp v105, v45, v45 quad_perm:[1,0,3,2] row_mask:0xf bank_mask:0xf bound_ctrl:1
	v_add_f32_dpp v106, v46, v46 quad_perm:[1,0,3,2] row_mask:0xf bank_mask:0xf bound_ctrl:1
	v_add_f32_dpp v107, v47, v47 quad_perm:[1,0,3,2] row_mask:0xf bank_mask:0xf bound_ctrl:1
	v_add_f32_dpp v100, v100, v100 quad_perm:[2,3,0,1] row_mask:0xf bank_mask:0xf bound_ctrl:1
	v_add_f32_dpp v101, v101, v101 quad_perm:[2,3,0,1] row_mask:0xf bank_mask:0xf bound_ctrl:1
	v_add_f32_dpp v102, v102, v102 quad_perm:[2,3,0,1] row_mask:0xf bank_mask:0xf bound_ctrl:1
	v_add_f32_dpp v103, v103, v103 quad_perm:[2,3,0,1] row_mask:0xf bank_mask:0xf bound_ctrl:1
	v_add_f32_dpp v104, v104, v104 quad_perm:[2,3,0,1] row_mask:0xf bank_mask:0xf bound_ctrl:1
	v_add_f32_dpp v105, v105, v105 quad_perm:[2,3,0,1] row_mask:0xf bank_mask:0xf bound_ctrl:1
	v_add_f32_dpp v106, v106, v106 quad_perm:[2,3,0,1] row_mask:0xf bank_mask:0xf bound_ctrl:1
	v_add_f32_dpp v107, v107, v107 quad_perm:[2,3,0,1] row_mask:0xf bank_mask:0xf bound_ctrl:1
	v_add_f32_dpp v100, v100, v100 row_half_mirror row_mask:0xf bank_mask:0xf bound_ctrl:1
	v_add_f32_dpp v101, v101, v101 row_half_mirror row_mask:0xf bank_mask:0xf bound_ctrl:1
	v_add_f32_dpp v102, v102, v102 row_half_mirror row_mask:0xf bank_mask:0xf bound_ctrl:1
	v_add_f32_dpp v103, v103, v103 row_half_mirror row_mask:0xf bank_mask:0xf bound_ctrl:1
	v_add_f32_dpp v104, v104, v104 row_half_mirror row_mask:0xf bank_mask:0xf bound_ctrl:1
	v_add_f32_dpp v105, v105, v105 row_half_mirror row_mask:0xf bank_mask:0xf bound_ctrl:1
	v_add_f32_dpp v106, v106, v106 row_half_mirror row_mask:0xf bank_mask:0xf bound_ctrl:1
; DI float wave_sum_fast(float v) { v = fdpp_add(v, 0); v = fdpp_add(v, 1); v = fdpp_add(v, 2); v = fdpp_add(v, 3); v = xor16_sum(v); return xor32_sum(v); }
; DI void rwkv_post(const Params& p, int l) {
;     ...
;       const float mean = wave_sum_fast(y[q]) * (1.f / 64.f);
;       const float dlt = y[q] - mean;
;       const float var = wave_sum_fast(dlt * dlt) * (1.f / 64.f);
;       float o = dlt * rsqrtf(var + 64e-5f) * lw + lb + bo[q] * v[q];
	v_add_f32_dpp v107, v107, v107 row_half_mirror row_mask:0xf bank_mask:0xf bound_ctrl:1
	v_add_f32_dpp v100, v100, v100 row_mirror row_mask:0xf bank_mask:0xf bound_ctrl:1
	v_add_f32_dpp v101, v101, v101 row_mirror row_mask:0xf bank_mask:0xf bound_ctrl:1
	v_add_f32_dpp v102, v102, v102 row_mirror row_mask:0xf bank_mask:0xf bound_ctrl:1
	v_add_f32_dpp v103, v103, v103 row_mirror row_mask:0xf bank_mask:0xf bound_ctrl:1
	v_add_f32_dpp v104, v104, v104 row_mirror row_mask:0xf bank_mask:0xf bound_ctrl:1
	v_add_f32_dpp v105, v105, v105 row_mirror row_mask:0xf bank_mask:0xf bound_ctrl:1
	v_add_f32_dpp v106, v106, v106 row_mirror row_mask:0xf bank_mask:0xf bound_ctrl:1
	v_add_f32_dpp v107, v107, v107 row_mirror row_mask:0xf bank_mask:0xf bound_ctrl:1
	v_mov_b32_e32 v108, v100
	v_mov_b32_e32 v109, v101
	v_mov_b32_e32 v110, v102
	v_mov_b32_e32 v111, v103
	v_mov_b32_e32 v112, v104
	v_mov_b32_e32 v113, v105
	v_mov_b32_e32 v114, v106
	v_mov_b32_e32 v115, v107
	v_permlane16_swap_b32_e32 v100, v108
	v_permlane16_swap_b32_e32 v101, v109
	v_permlane16_swap_b32_e32 v102, v110
	v_permlane16_swap_b32_e32 v103, v111
	v_permlane16_swap_b32_e32 v104, v112
	v_permlane16_swap_b32_e32 v105, v113
	v_permlane16_swap_b32_e32 v106, v114
	v_permlane16_swap_b32_e32 v107, v115
	v_add_f32_e32 v100, v100, v108
	v_add_f32_e32 v101, v101, v109
	v_add_f32_e32 v102, v102, v110
	v_add_f32_e32 v103, v103, v111
	v_add_f32_e32 v104, v104, v112
	v_add_f32_e32 v105, v105, v113
	v_add_f32_e32 v106, v106, v114
	v_add_f32_e32 v107, v107, v115
	v_mov_b32_e32 v108, v100
	v_mov_b32_e32 v109, v101
	v_mov_b32_e32 v110, v102
	v_mov_b32_e32 v111, v103
	v_mov_b32_e32 v112, v104
	v_mov_b32_e32 v113, v105
	v_mov_b32_e32 v114, v106
	v_mov_b32_e32 v115, v107
	v_permlane32_swap_b32_e32 v100, v108
	v_permlane32_swap_b32_e32 v101, v109
	v_permlane32_swap_b32_e32 v102, v110
	v_permlane32_swap_b32_e32 v103, v111
	v_permlane32_swap_b32_e32 v104, v112
	v_permlane32_swap_b32_e32 v105, v113
	v_permlane32_swap_b32_e32 v106, v114
	v_permlane32_swap_b32_e32 v107, v115
	v_add_f32_e32 v100, v100, v108
	v_add_f32_e32 v101, v101, v109
	v_add_f32_e32 v102, v102, v110
	v_add_f32_e32 v103, v103, v111
	v_add_f32_e32 v104, v104, v112
	v_add_f32_e32 v105, v105, v113
	v_add_f32_e32 v106, v106, v114
	v_add_f32_e32 v107, v107, v115
	v_fmac_f32_e32 v40, 0xbc800000, v100
	v_fmac_f32_e32 v41, 0xbc800000, v101
	v_fmac_f32_e32 v42, 0xbc800000, v102
	v_fmac_f32_e32 v43, 0xbc800000, v103
	v_fmac_f32_e32 v44, 0xbc800000, v104
	v_fmac_f32_e32 v45, 0xbc800000, v105
	v_fmac_f32_e32 v46, 0xbc800000, v106
	v_fmac_f32_e32 v47, 0xbc800000, v107
	v_mul_f32_e32 v108, v40, v40
	v_mul_f32_e32 v109, v41, v41
	v_mul_f32_e32 v110, v42, v42
	v_mul_f32_e32 v111, v43, v43
	v_mul_f32_e32 v112, v44, v44
	v_mul_f32_e32 v113, v45, v45
	v_mul_f32_e32 v114, v46, v46
	v_mul_f32_e32 v115, v47, v47
	v_add_f32_dpp v100, v108, v108 quad_perm:[1,0,3,2] row_mask:0xf bank_mask:0xf bound_ctrl:1
	v_add_f32_dpp v101, v109, v109 quad_perm:[1,0,3,2] row_mask:0xf bank_mask:0xf bound_ctrl:1
	v_add_f32_dpp v102, v110, v110 quad_perm:[1,0,3,2] row_mask:0xf bank_mask:0xf bound_ctrl:1
	v_add_f32_dpp v103, v111, v111 quad_perm:[1,0,3,2] row_mask:0xf bank_mask:0xf bound_ctrl:1
	v_add_f32_dpp v104, v112, v112 quad_perm:[1,0,3,2] row_mask:0xf bank_mask:0xf bound_ctrl:1
	v_add_f32_dpp v105, v113, v113 quad_perm:[1,0,3,2] row_mask:0xf bank_mask:0xf bound_ctrl:1
	v_add_f32_dpp v106, v114, v114 quad_perm:[1,0,3,2] row_mask:0xf bank_mask:0xf bound_ctrl:1
	v_add_f32_dpp v107, v115, v115 quad_perm:[1,0,3,2] row_mask:0xf bank_mask:0xf bound_ctrl:1
	v_add_f32_dpp v100, v100, v100 quad_perm:[2,3,0,1] row_mask:0xf bank_mask:0xf bound_ctrl:1
	v_add_f32_dpp v101, v101, v101 quad_perm:[2,3,0,1] row_mask:0xf bank_mask:0xf bound_ctrl:1
	v_add_f32_dpp v102, v102, v102 quad_perm:[2,3,0,1] row_mask:0xf bank_mask:0xf bound_ctrl:1
	v_add_f32_dpp v103, v103, v103 quad_perm:[2,3,0,1] row_mask:0xf bank_mask:0xf bound_ctrl:1
	v_add_f32_dpp v104, v104, v104 quad_perm:[2,3,0,1] row_mask:0xf bank_mask:0xf bound_ctrl:1
	v_add_f32_dpp v105, v105, v105 quad_perm:[2,3,0,1] row_mask:0xf bank_mask:0xf bound_ctrl:1
	v_add_f32_dpp v106, v106, v106 quad_perm:[2,3,0,1] row_mask:0xf bank_mask:0xf bound_ctrl:1
	v_add_f32_dpp v107, v107, v107 quad_perm:[2,3,0,1] row_mask:0xf bank_mask:0xf bound_ctrl:1
	v_add_f32_dpp v100, v100, v100 row_half_mirror row_mask:0xf bank_mask:0xf bound_ctrl:1
	v_add_f32_dpp v101, v101, v101 row_half_mirror row_mask:0xf bank_mask:0xf bound_ctrl:1
	v_add_f32_dpp v102, v102, v102 row_half_mirror row_mask:0xf bank_mask:0xf bound_ctrl:1
	v_add_f32_dpp v103, v103, v103 row_half_mirror row_mask:0xf bank_mask:0xf bound_ctrl:1
	v_add_f32_dpp v104, v104, v104 row_half_mirror row_mask:0xf bank_mask:0xf bound_ctrl:1
	v_add_f32_dpp v105, v105, v105 row_half_mirror row_mask:0xf bank_mask:0xf bound_ctrl:1
	v_add_f32_dpp v106, v106, v106 row_half_mirror row_mask:0xf bank_mask:0xf bound_ctrl:1
	v_add_f32_dpp v107, v107, v107 row_half_mirror row_mask:0xf bank_mask:0xf bound_ctrl:1
	v_add_f32_dpp v100, v100, v100 row_mirror row_mask:0xf bank_mask:0xf bound_ctrl:1
	v_add_f32_dpp v101, v101, v101 row_mirror row_mask:0xf bank_mask:0xf bound_ctrl:1
	v_add_f32_dpp v102, v102, v102 row_mirror row_mask:0xf bank_mask:0xf bound_ctrl:1
; DI bf16_t f2bf(float a) { return (bf16_t)(pack2(a, 0.f) & 0xffffu); }
; DI float siluf_(float x) { return x * __builtin_amdgcn_rcpf(1.f + __expf(-x)); }
; DI float wave_sum_fast(float v) { v = fdpp_add(v, 0); v = fdpp_add(v, 1); v = fdpp_add(v, 2); v = fdpp_add(v, 3); v = xor16_sum(v); return xor32_sum(v); }
; DI void rwkv_post(const Params& p, int l) {
;     ...
;       const float mean = wave_sum_fast(y[q]) * (1.f / 64.f);
;       const float dlt = y[q] - mean;
;       const float var = wave_sum_fast(dlt * dlt) * (1.f / 64.f);
;       float o = dlt * rsqrtf(var + 64e-5f) * lw + lb + bo[q] * v[q];
;       o *= siluf_(z[q]);
;       hw[m * HS + C_CZ + hd * 64 + lane] = f2bf(o);
;     }
;   }
	v_add_f32_dpp v103, v103, v103 row_mirror row_mask:0xf bank_mask:0xf bound_ctrl:1
	v_add_f32_dpp v104, v104, v104 row_mirror row_mask:0xf bank_mask:0xf bound_ctrl:1
	v_add_f32_dpp v105, v105, v105 row_mirror row_mask:0xf bank_mask:0xf bound_ctrl:1
	v_add_f32_dpp v106, v106, v106 row_mirror row_mask:0xf bank_mask:0xf bound_ctrl:1
	v_add_f32_dpp v107, v107, v107 row_mirror row_mask:0xf bank_mask:0xf bound_ctrl:1
	v_mov_b32_e32 v108, v100
	v_mov_b32_e32 v109, v101
	v_mov_b32_e32 v110, v102
	v_mov_b32_e32 v111, v103
	v_mov_b32_e32 v112, v104
	v_mov_b32_e32 v113, v105
	v_mov_b32_e32 v114, v106
	v_mov_b32_e32 v115, v107
	v_permlane16_swap_b32_e32 v100, v108
	v_permlane16_swap_b32_e32 v101, v109
	v_permlane16_swap_b32_e32 v102, v110
	v_permlane16_swap_b32_e32 v103, v111
	v_permlane16_swap_b32_e32 v104, v112
	v_permlane16_swap_b32_e32 v105, v113
	v_permlane16_swap_b32_e32 v106, v114
	v_permlane16_swap_b32_e32 v107, v115
	v_add_f32_e32 v100, v100, v108
	v_add_f32_e32 v101, v101, v109
	v_add_f32_e32 v102, v102, v110
	v_add_f32_e32 v103, v103, v111
	v_add_f32_e32 v104, v104, v112
	v_add_f32_e32 v105, v105, v113
	v_add_f32_e32 v106, v106, v114
	v_add_f32_e32 v107, v107, v115
	v_mov_b32_e32 v108, v100
	v_mov_b32_e32 v109, v101
	v_mov_b32_e32 v110, v102
	v_mov_b32_e32 v111, v103
	v_mov_b32_e32 v112, v104
	v_mov_b32_e32 v113, v105
	v_mov_b32_e32 v114, v106
	v_mov_b32_e32 v115, v107
	v_permlane32_swap_b32_e32 v100, v108
	v_permlane32_swap_b32_e32 v101, v109
	v_permlane32_swap_b32_e32 v102, v110
	v_permlane32_swap_b32_e32 v103, v111
	v_permlane32_swap_b32_e32 v104, v112
	v_permlane32_swap_b32_e32 v105, v113
	v_permlane32_swap_b32_e32 v106, v114
	v_permlane32_swap_b32_e32 v107, v115
	v_add_f32_e32 v100, v100, v108
	v_add_f32_e32 v101, v101, v109
	v_add_f32_e32 v102, v102, v110
	v_add_f32_e32 v103, v103, v111
	v_add_f32_e32 v104, v104, v112
	v_add_f32_e32 v105, v105, v113
	v_add_f32_e32 v106, v106, v114
	v_add_f32_e32 v107, v107, v115
	v_fmamk_f32 v100, v100, 0x3c800000, v116
	v_fmamk_f32 v101, v101, 0x3c800000, v116
	v_fmamk_f32 v102, v102, 0x3c800000, v116
	v_fmamk_f32 v103, v103, 0x3c800000, v116
	v_fmamk_f32 v104, v104, 0x3c800000, v116
	v_fmamk_f32 v105, v105, 0x3c800000, v116
	v_fmamk_f32 v106, v106, 0x3c800000, v116
	v_fmamk_f32 v107, v107, 0x3c800000, v116
	v_rsq_f32_e32 v100, v100
	v_rsq_f32_e32 v101, v101
	v_rsq_f32_e32 v102, v102
	v_rsq_f32_e32 v103, v103
	v_rsq_f32_e32 v104, v104
	v_rsq_f32_e32 v105, v105
	v_rsq_f32_e32 v106, v106
	v_rsq_f32_e32 v107, v107
	v_mul_f32_e32 v108, 0xbfb8aa3b, v56
	v_mul_f32_e32 v109, 0xbfb8aa3b, v57
	v_mul_f32_e32 v110, 0xbfb8aa3b, v58
	v_mul_f32_e32 v111, 0xbfb8aa3b, v59
	v_mul_f32_e32 v112, 0xbfb8aa3b, v60
	v_mul_f32_e32 v113, 0xbfb8aa3b, v61
	v_mul_f32_e32 v114, 0xbfb8aa3b, v62
	v_mul_f32_e32 v115, 0xbfb8aa3b, v63
	v_exp_f32_e32 v108, v108
	v_exp_f32_e32 v109, v109
	v_exp_f32_e32 v110, v110
	v_exp_f32_e32 v111, v111
	v_exp_f32_e32 v112, v112
	v_exp_f32_e32 v113, v113
	v_exp_f32_e32 v114, v114
	v_exp_f32_e32 v115, v115
	v_mul_f32_e32 v40, v40, v100
	v_mul_f32_e32 v41, v41, v101
	v_mul_f32_e32 v42, v42, v102
	v_mul_f32_e32 v43, v43, v103
	v_mul_f32_e32 v44, v44, v104
	v_mul_f32_e32 v45, v45, v105
	v_mul_f32_e32 v46, v46, v106
	v_mul_f32_e32 v47, v47, v107
	v_add_f32_e32 v108, 1.0, v108
	v_add_f32_e32 v109, 1.0, v109
	v_add_f32_e32 v110, 1.0, v110
	v_add_f32_e32 v111, 1.0, v111
	v_add_f32_e32 v112, 1.0, v112
	v_add_f32_e32 v113, 1.0, v113
	v_add_f32_e32 v114, 1.0, v114
	v_add_f32_e32 v115, 1.0, v115
	v_rcp_f32_e32 v108, v108
	v_rcp_f32_e32 v109, v109
	v_rcp_f32_e32 v110, v110
	v_rcp_f32_e32 v111, v111
	v_rcp_f32_e32 v112, v112
	v_rcp_f32_e32 v113, v113
	v_rcp_f32_e32 v114, v114
	v_rcp_f32_e32 v115, v115
	v_fma_f32 v40, v31, v40, v32
	v_fma_f32 v41, v31, v41, v32
	v_fma_f32 v42, v31, v42, v32
	v_fma_f32 v43, v31, v43, v32
	v_fma_f32 v44, v31, v44, v32
	v_fma_f32 v45, v31, v45, v32
	v_fma_f32 v46, v31, v46, v32
	v_fma_f32 v47, v31, v47, v32
	v_fmac_f32_e32 v40, v64, v48
	v_fmac_f32_e32 v41, v65, v49
	v_fmac_f32_e32 v42, v66, v50
	v_fmac_f32_e32 v43, v67, v51
	v_fmac_f32_e32 v44, v68, v52
	v_fmac_f32_e32 v45, v69, v53
	v_fmac_f32_e32 v46, v70, v54
	v_fmac_f32_e32 v47, v71, v55
	v_mul_f32_e32 v108, v108, v56
	v_mul_f32_e32 v109, v109, v57
	v_mul_f32_e32 v110, v110, v58
	v_mul_f32_e32 v111, v111, v59
	v_mul_f32_e32 v112, v112, v60
	v_mul_f32_e32 v113, v113, v61
	v_mul_f32_e32 v114, v114, v62
	v_mul_f32_e32 v115, v115, v63
	v_mul_f32_e32 v40, v108, v40
	v_mul_f32_e32 v41, v109, v41
	v_mul_f32_e32 v42, v110, v42
	v_mul_f32_e32 v43, v111, v43
	v_mul_f32_e32 v44, v112, v44
	v_mul_f32_e32 v45, v113, v45
	v_mul_f32_e32 v46, v114, v46
	v_mul_f32_e32 v47, v115, v47
	v_cvt_pk_bf16_f32 v40, v40, v40
	v_cvt_pk_bf16_f32 v41, v41, v41
	v_cvt_pk_bf16_f32 v42, v42, v42
	v_cvt_pk_bf16_f32 v43, v43, v43
	v_cvt_pk_bf16_f32 v44, v44, v44
	v_cvt_pk_bf16_f32 v45, v45, v45
	v_cvt_pk_bf16_f32 v46, v46, v46
	v_cvt_pk_bf16_f32 v47, v47, v47
	global_store_short v[72:73], v40, off
	global_store_short v[74:75], v41, off
	global_store_short v[76:77], v42, off
	global_store_short v[78:79], v43, off
	global_store_short v[80:81], v44, off
	global_store_short v[82:83], v45, off
	global_store_short v[84:85], v46, off
	global_store_short v[86:87], v47, off
	s_add_i32 s2, s2, s4
	s_cmpk_lt_i32 s2, 0x400
	s_cbranch_scc1 .LBB0_862
	s_movk_i32 s87, 0x1e00
